# adds FFN-in unit epilogues: the leading half's alignment barrier moved behind the first half of its epilogue
# baseline (speedup 1.0000x reference)
; __device__ __forceinline__ unsigned cvt_pk_bf16(float lo, float hi) { unsigned r; asm volatile("v_cvt_pk_bf16_f32 %0, %1, %2" : "=v"(r) : "v"(lo), "v"(hi)); return r; }
; #define PG8_BAR __builtin_amdgcn_s_barrier()
;     __device__ __forceinline__ void half(const f32x4 (&acc)[2][4][2], int pm, int ai, int pn, int wr, int wc, int fr, int fq) const {
;         const int row0 = pm * BM + wr * 64 + fr, col0 = pn * HALF + wc * 32 + 8 * fq;
;         {
; #pragma unroll
;             for (int m = 0; m < 4; ++m) {
;                 float a[8], e[8];
; #pragma unroll
;                 for (int q = 0; q < 8; ++q) a[q] = acc[0][m][q >> 2][q & 3];
; #pragma unroll
;                 for (int q = 0; q < 8; ++q) e[q] = __builtin_amdgcn_exp2f(-a[q]);
; #pragma unroll
;                 for (int q = 0; q < 8; ++q) e[q] += 1.f;
; #pragma unroll
;                 for (int q = 0; q < 8; ++q) e[q] = __builtin_amdgcn_rcpf(e[q]);
; #pragma unroll
;                 for (int q = 0; q < 8; ++q) a[q] = a[q] * acc[1][m][q >> 2][q & 3] * e[q];
;                 u32x4 w; w.x = cvt_pk_bf16(a[0], a[1]); w.y = cvt_pk_bf16(a[2], a[3]); w.z = cvt_pk_bf16(a[4], a[5]); w.w = cvt_pk_bf16(a[6], a[7]);
;                 const int row = row0 + ai * HALF + m * 16;
;                 bf16_t* dst = O + (((size_t)(row >> 8) * (ldc >> 6) + (col0 >> 6)) * 256 + (row & 255)) * 64 + (col0 & 63);
;                 if (wt) asm volatile("global_store_dwordx4 %0, %1, off sc1\n\ts_nop 1" :: "v"(dst), "v"(w) : "memory"); else *(u32x4*)dst = w; }
; template <class Epi, class Sched, bool ALIGN_EPI = false, bool SP2 = false>
; __device__ __forceinline__ void gemm_phase(PG8_LAS unsigned char* lds, const Gemm g, const Sched& S, const Epi& E) {
;     ...
;         if constexpr (ALIGN_EPI) { if (wr == 0) PG8_BAR; }
.LBB0_303:
	v_exp_f32_e64 v159, -v120
	v_exp_f32_e64 v160, -v121
	v_exp_f32_e64 v155, -v124
	v_exp_f32_e64 v156, -v125
	v_exp_f32_e64 v157, -v126
	v_exp_f32_e64 v161, -v122
	v_exp_f32_e64 v158, -v127
	v_exp_f32_e64 v162, -v123
	s_lshl_b32 s4, s54, 8
	v_add_f32_e32 v159, 1.0, v159
	s_lshl_b32 s5, s52, 7
	s_add_i32 s12, s4, s11
	v_add_f32_e32 v160, 1.0, v160
	v_rcp_f32_e32 v159, v159
	s_or_b32 s5, s5, s33
	s_ashr_i32 s12, s12, 8
	v_add_f32_e32 v155, 1.0, v155
	v_add_f32_e32 v156, 1.0, v156
	v_add_f32_e32 v157, 1.0, v157
	v_add_f32_e32 v161, 1.0, v161
	v_rcp_f32_e32 v160, v160
	s_ashr_i32 s50, s5, 6
	v_add_f32_e32 v158, 1.0, v158
	v_add_f32_e32 v162, 1.0, v162
	v_rcp_f32_e32 v155, v155
	v_rcp_f32_e32 v156, v156
	v_rcp_f32_e32 v157, v157
	v_rcp_f32_e32 v161, v161
	s_mulk_i32 s12, 0x58
	s_ashr_i32 s51, s50, 31
	v_rcp_f32_e32 v158, v158
	v_rcp_f32_e32 v162, v162
	v_mul_f32_e32 v112, v112, v120
	s_ashr_i32 s5, s12, 31
	v_mul_f32_e32 v120, v112, v159
	v_mul_f32_e32 v112, v113, v121
	s_add_u32 s12, s12, s50
	v_mul_f32_e32 v116, v116, v124
	v_mul_f32_e32 v117, v117, v125
	v_mul_f32_e32 v118, v118, v126
	v_mul_f32_e32 v121, v112, v160
	v_mul_f32_e32 v112, v114, v122
	s_addc_u32 s13, s5, s51
	v_mul_f32_e32 v116, v116, v155
	v_mul_f32_e32 v117, v117, v156
	v_mul_f32_e32 v118, v118, v157
	v_mul_f32_e32 v119, v119, v127
	v_mul_f32_e32 v122, v112, v161
	v_mul_f32_e32 v112, v115, v123
	s_lshl_b64 s[12:13], s[12:13], 15
	v_mul_f32_e32 v119, v119, v158
	v_mul_f32_e32 v115, v112, v162
	v_cvt_pk_bf16_f32 v112, v116, v117
	v_cvt_pk_bf16_f32 v113, v118, v119
	v_lshl_add_u64 v[116:117], v[138:139], 0, s[12:13]
	v_exp_f32_e64 v118, -v104
	v_lshl_add_u64 v[116:117], v[116:117], 0, v[136:137]
	v_exp_f32_e64 v119, -v105
	v_cvt_pk_bf16_f32 v114, v120, v121
	v_cvt_pk_bf16_f32 v115, v122, v115
	global_store_dwordx4 v[116:117], v[112:115], off
	v_exp_f32_e64 v120, -v106
	v_exp_f32_e64 v121, -v107
	v_exp_f32_e64 v112, -v108
	v_exp_f32_e64 v113, -v109
	v_exp_f32_e64 v114, -v110
	v_exp_f32_e64 v115, -v111
	v_add_f32_e32 v118, 1.0, v118
	v_add_f32_e32 v119, 1.0, v119
	v_rcp_f32_e32 v118, v118
	v_add_f32_e32 v112, 1.0, v112
	v_add_f32_e32 v120, 1.0, v120
	v_rcp_f32_e32 v119, v119
	v_add_f32_e32 v113, 1.0, v113
	v_add_f32_e32 v121, 1.0, v121
	v_rcp_f32_e32 v112, v112
	v_rcp_f32_e32 v120, v120
	v_add_f32_e32 v114, 1.0, v114
	v_add_f32_e32 v115, 1.0, v115
	v_rcp_f32_e32 v113, v113
	v_rcp_f32_e32 v121, v121
	v_mul_f32_e32 v96, v96, v104
	v_rcp_f32_e32 v114, v114
	v_rcp_f32_e32 v115, v115
	v_mul_f32_e32 v104, v96, v118
	v_mul_f32_e32 v96, v97, v105
	v_mul_f32_e32 v100, v100, v108
	v_mul_f32_e32 v105, v96, v119
	v_mul_f32_e32 v96, v98, v106
	v_mul_f32_e32 v100, v100, v112
	v_mul_f32_e32 v101, v101, v109
	v_mul_f32_e32 v106, v96, v120
	v_mul_f32_e32 v96, v99, v107
	v_mul_f32_e32 v101, v101, v113
	v_mul_f32_e32 v102, v102, v110
	v_mul_f32_e32 v103, v103, v111
	v_mul_f32_e32 v99, v96, v121
	v_cvt_pk_bf16_f32 v96, v100, v101
	v_exp_f32_e64 v100, -v88
	v_mul_f32_e32 v102, v102, v114
	v_mul_f32_e32 v103, v103, v115
	v_cvt_pk_bf16_f32 v97, v102, v103
	v_cvt_pk_bf16_f32 v98, v104, v105
	v_exp_f32_e64 v101, -v89
	v_cvt_pk_bf16_f32 v99, v106, v99
	global_store_dwordx4 v[116:117], v[96:99], off offset:2048
	v_exp_f32_e64 v102, -v90
	v_exp_f32_e64 v103, -v91
	v_exp_f32_e64 v96, -v92
	v_exp_f32_e64 v98, -v94
	v_exp_f32_e64 v97, -v93
	v_exp_f32_e64 v99, -v95
	v_add_f32_e32 v100, 1.0, v100
	v_add_f32_e32 v101, 1.0, v101
	v_rcp_f32_e32 v100, v100
	v_add_f32_e32 v96, 1.0, v96
	v_add_f32_e32 v98, 1.0, v98
	v_add_f32_e32 v102, 1.0, v102
	v_rcp_f32_e32 v101, v101
	v_add_f32_e32 v97, 1.0, v97
	v_add_f32_e32 v99, 1.0, v99
	v_add_f32_e32 v103, 1.0, v103
	v_rcp_f32_e32 v96, v96
	v_rcp_f32_e32 v98, v98
	v_rcp_f32_e32 v102, v102
	v_rcp_f32_e32 v97, v97
	v_rcp_f32_e32 v99, v99
	v_rcp_f32_e32 v103, v103
	v_mul_f32_e32 v80, v80, v88
	v_mul_f32_e32 v88, v80, v100
	v_mul_f32_e32 v80, v81, v89
	v_mul_f32_e32 v84, v84, v92
	v_mul_f32_e32 v86, v86, v94
	v_mul_f32_e32 v89, v80, v101
	v_mul_f32_e32 v80, v82, v90
	v_mul_f32_e32 v84, v84, v96
	v_mul_f32_e32 v85, v85, v93
	v_mul_f32_e32 v86, v86, v98
	v_mul_f32_e32 v87, v87, v95
	v_mul_f32_e32 v90, v80, v102
	v_mul_f32_e32 v80, v83, v91
	v_mul_f32_e32 v85, v85, v97
	v_mul_f32_e32 v87, v87, v99
	v_mul_f32_e32 v83, v80, v103
	v_cvt_pk_bf16_f32 v80, v84, v85
	v_cvt_pk_bf16_f32 v81, v86, v87
	v_add_co_u32_e32 v84, vcc, s60, v116
	v_exp_f32_e64 v86, -v72
	s_nop 0
	v_addc_co_u32_e32 v85, vcc, 0, v117, vcc
	v_exp_f32_e64 v87, -v73
	v_cvt_pk_bf16_f32 v82, v88, v89
	v_cvt_pk_bf16_f32 v83, v90, v83
	global_store_dwordx4 v[84:85], v[80:83], off
	v_exp_f32_e64 v88, -v74
	v_exp_f32_e64 v89, -v75
	v_exp_f32_e64 v81, -v77
	v_exp_f32_e64 v80, -v76
	v_exp_f32_e64 v82, -v78
	v_exp_f32_e64 v83, -v79
	v_add_f32_e32 v86, 1.0, v86
	v_add_f32_e32 v87, 1.0, v87
	v_rcp_f32_e32 v86, v86
	v_add_f32_e32 v81, 1.0, v81
	v_add_f32_e32 v88, 1.0, v88
	v_rcp_f32_e32 v87, v87
	v_add_f32_e32 v80, 1.0, v80
	v_add_f32_e32 v82, 1.0, v82
	v_add_f32_e32 v89, 1.0, v89
	v_rcp_f32_e32 v81, v81
	v_rcp_f32_e32 v88, v88
	v_add_f32_e32 v83, 1.0, v83
	v_rcp_f32_e32 v80, v80
	v_rcp_f32_e32 v82, v82
	v_rcp_f32_e32 v89, v89
	v_mul_f32_e32 v64, v64, v72
	v_rcp_f32_e32 v83, v83
	v_mul_f32_e32 v72, v64, v86
	v_mul_f32_e32 v64, v65, v73
	v_mul_f32_e32 v69, v69, v77
	v_mul_f32_e32 v73, v64, v87
	v_mul_f32_e32 v64, v66, v74
	v_mul_f32_e32 v68, v68, v76
	v_mul_f32_e32 v69, v69, v81
	v_mul_f32_e32 v70, v70, v78
	v_mul_f32_e32 v74, v64, v88
	v_mul_f32_e32 v64, v67, v75
	v_mul_f32_e32 v68, v68, v80
	v_mul_f32_e32 v70, v70, v82
	v_mul_f32_e32 v71, v71, v79
	v_mul_f32_e32 v67, v64, v89
	v_cvt_pk_bf16_f32 v64, v68, v69
	v_exp_f32_e64 v69, -v56
	v_mul_f32_e32 v71, v71, v83
	v_cvt_pk_bf16_f32 v65, v70, v71
	v_exp_f32_e64 v70, -v57
	v_cvt_pk_bf16_f32 v66, v72, v73
	v_cvt_pk_bf16_f32 v67, v74, v67
	global_store_dwordx4 v[84:85], v[64:67], off offset:2048
	s_and_b64 vcc, exec, s[38:39]
	s_cbranch_vccz .Lepi_303
	s_barrier
; __device__ __forceinline__ unsigned cvt_pk_bf16(float lo, float hi) { unsigned r; asm volatile("v_cvt_pk_bf16_f32 %0, %1, %2" : "=v"(r) : "v"(lo), "v"(hi)); return r; }
; #define PG8_BAR __builtin_amdgcn_s_barrier()
;     __device__ __forceinline__ void half(const f32x4 (&acc)[2][4][2], int pm, int ai, int pn, int wr, int wc, int fr, int fq) const {
;         const int row0 = pm * BM + wr * 64 + fr, col0 = pn * HALF + wc * 32 + 8 * fq;
;         {
; #pragma unroll
;             for (int m = 0; m < 4; ++m) {
;                 float a[8], e[8];
; #pragma unroll
;                 for (int q = 0; q < 8; ++q) a[q] = acc[0][m][q >> 2][q & 3];
; #pragma unroll
;                 for (int q = 0; q < 8; ++q) e[q] = __builtin_amdgcn_exp2f(-a[q]);
; #pragma unroll
;                 for (int q = 0; q < 8; ++q) e[q] += 1.f;
; #pragma unroll
;                 for (int q = 0; q < 8; ++q) e[q] = __builtin_amdgcn_rcpf(e[q]);
; #pragma unroll
;                 for (int q = 0; q < 8; ++q) a[q] = a[q] * acc[1][m][q >> 2][q & 3] * e[q];
;                 u32x4 w; w.x = cvt_pk_bf16(a[0], a[1]); w.y = cvt_pk_bf16(a[2], a[3]); w.z = cvt_pk_bf16(a[4], a[5]); w.w = cvt_pk_bf16(a[6], a[7]);
;                 const int row = row0 + ai * HALF + m * 16;
;                 bf16_t* dst = O + (((size_t)(row >> 8) * (ldc >> 6) + (col0 >> 6)) * 256 + (row & 255)) * 64 + (col0 & 63);
;                 if (wt) asm volatile("global_store_dwordx4 %0, %1, off sc1\n\ts_nop 1" :: "v"(dst), "v"(w) : "memory"); else *(u32x4*)dst = w; }
; template <class Epi, class Sched, bool ALIGN_EPI = false, bool SP2 = false>
; __device__ __forceinline__ void gemm_phase(PG8_LAS unsigned char* lds, const Gemm g, const Sched& S, const Epi& E) {
;     ...
;         if constexpr (ALIGN_EPI) { if (wr == 0) PG8_BAR; }
;         if constexpr (!Epi::AFTER_DRAIN) { E(acc, cur, wr, wc, fr, fq); S.done(cur); }
;         if (!has_next) break;
; #pragma unroll
;         for (int a = 0; a < 2; ++a)
; #pragma unroll
;             for (int b = 0; b < 2; ++b)
; #pragma unroll
;                 for (int m = 0; m < 4; ++m)
; #pragma unroll
;                     for (int n = 0; n < 2; ++n) acc[a][b][m][n] = (f32x4){0.f, 0.f, 0.f, 0.f};
;         cur = nxt; cA = nA; cB = nB; ++ui;
;         if constexpr (ALIGN_EPI) { if (wr == 1) PG8_BAR; }
.Lepi_303:
	v_exp_f32_e64 v71, -v58
	v_exp_f32_e64 v72, -v59
	v_exp_f32_e64 v65, -v60
	v_exp_f32_e64 v66, -v61
	v_add_f32_e32 v69, 1.0, v69
	v_add_f32_e32 v70, 1.0, v70
	v_rcp_f32_e32 v69, v69
	v_exp_f32_e64 v67, -v62
	v_add_f32_e32 v65, 1.0, v65
	v_add_f32_e32 v71, 1.0, v71
	v_rcp_f32_e32 v70, v70
	v_exp_f32_e64 v68, -v63
	v_add_f32_e32 v66, 1.0, v66
	v_add_f32_e32 v72, 1.0, v72
	v_rcp_f32_e32 v65, v65
	v_rcp_f32_e32 v71, v71
	v_rcp_f32_e32 v66, v66
	v_rcp_f32_e32 v72, v72
	v_mul_f32_e32 v48, v48, v56
	v_mul_f32_e32 v56, v48, v69
	v_mul_f32_e32 v48, v49, v57
	v_add_u32_e32 v64, s4, v151
	v_add_f32_e32 v67, 1.0, v67
	v_mul_f32_e32 v52, v52, v60
	v_mul_f32_e32 v57, v48, v70
	v_mul_f32_e32 v48, v50, v58
	v_lshrrev_b32_e32 v64, 8, v64
	v_add_f32_e32 v68, 1.0, v68
	v_rcp_f32_e32 v67, v67
	v_mul_f32_e32 v52, v52, v65
	v_mul_f32_e32 v53, v53, v61
	v_mul_f32_e32 v58, v48, v71
	v_mul_f32_e32 v48, v51, v59
	v_rcp_f32_e32 v68, v68
	v_mul_f32_e32 v53, v53, v66
	v_mul_f32_e32 v51, v48, v72
	v_cvt_pk_bf16_f32 v48, v52, v53
	v_mul_i32_i24_e32 v52, 0x58, v64
	v_ashrrev_i32_e32 v53, 31, v52
	v_mul_f32_e32 v54, v54, v62
	v_lshl_add_u64 v[52:53], v[52:53], 0, s[50:51]
	v_mul_f32_e32 v54, v54, v67
	v_mul_f32_e32 v55, v55, v63
	v_lshlrev_b64 v[52:53], 15, v[52:53]
	v_mul_f32_e32 v55, v55, v68
	v_cvt_pk_bf16_f32 v49, v54, v55
	v_lshl_add_u64 v[52:53], v[140:141], 0, v[52:53]
	v_exp_f32_e64 v54, -v40
	v_lshl_add_u64 v[52:53], v[52:53], 0, v[136:137]
	v_exp_f32_e64 v55, -v41
	v_cvt_pk_bf16_f32 v50, v56, v57
	v_cvt_pk_bf16_f32 v51, v58, v51
	global_store_dwordx4 v[52:53], v[48:51], off
	v_exp_f32_e64 v56, -v42
	v_exp_f32_e64 v57, -v43
	v_exp_f32_e64 v48, -v44
	v_exp_f32_e64 v49, -v45
	v_exp_f32_e64 v50, -v46
	v_exp_f32_e64 v51, -v47
	v_add_f32_e32 v54, 1.0, v54
	v_add_f32_e32 v55, 1.0, v55
	v_rcp_f32_e32 v54, v54
	v_add_f32_e32 v48, 1.0, v48
	v_add_f32_e32 v56, 1.0, v56
	v_rcp_f32_e32 v55, v55
	v_add_f32_e32 v49, 1.0, v49
	v_add_f32_e32 v57, 1.0, v57
	v_rcp_f32_e32 v48, v48
	v_rcp_f32_e32 v56, v56
	v_add_f32_e32 v50, 1.0, v50
	v_add_f32_e32 v51, 1.0, v51
	v_rcp_f32_e32 v49, v49
	v_rcp_f32_e32 v57, v57
	v_mul_f32_e32 v32, v32, v40
	v_rcp_f32_e32 v50, v50
	v_rcp_f32_e32 v51, v51
	v_mul_f32_e32 v40, v32, v54
	v_mul_f32_e32 v32, v33, v41
	v_mul_f32_e32 v36, v36, v44
	v_mul_f32_e32 v41, v32, v55
	v_mul_f32_e32 v32, v34, v42
	v_mul_f32_e32 v36, v36, v48
	v_mul_f32_e32 v37, v37, v45
	v_mul_f32_e32 v42, v32, v56
	v_mul_f32_e32 v32, v35, v43
	v_mul_f32_e32 v37, v37, v49
	v_mul_f32_e32 v38, v38, v46
	v_mul_f32_e32 v39, v39, v47
	v_mul_f32_e32 v35, v32, v57
	v_cvt_pk_bf16_f32 v32, v36, v37
	v_exp_f32_e64 v36, -v24
	v_mul_f32_e32 v38, v38, v50
	v_mul_f32_e32 v39, v39, v51
	v_cvt_pk_bf16_f32 v33, v38, v39
	v_cvt_pk_bf16_f32 v34, v40, v41
	v_exp_f32_e64 v37, -v25
	v_cvt_pk_bf16_f32 v35, v42, v35
	global_store_dwordx4 v[52:53], v[32:35], off offset:2048
	v_exp_f32_e64 v38, -v26
	v_exp_f32_e64 v39, -v27
	v_exp_f32_e64 v34, -v30
	v_exp_f32_e64 v32, -v28
	v_exp_f32_e64 v33, -v29
	v_exp_f32_e64 v35, -v31
	v_add_f32_e32 v36, 1.0, v36
	v_add_f32_e32 v37, 1.0, v37
	v_rcp_f32_e32 v36, v36
	v_add_f32_e32 v34, 1.0, v34
	v_add_f32_e32 v38, 1.0, v38
	v_rcp_f32_e32 v37, v37
	v_add_f32_e32 v32, 1.0, v32
	v_add_f32_e32 v33, 1.0, v33
	v_add_f32_e32 v35, 1.0, v35
	v_add_f32_e32 v39, 1.0, v39
	v_rcp_f32_e32 v34, v34
	v_rcp_f32_e32 v38, v38
	v_rcp_f32_e32 v32, v32
	v_rcp_f32_e32 v33, v33
	v_rcp_f32_e32 v35, v35
	v_rcp_f32_e32 v39, v39
	v_mul_f32_e32 v16, v16, v24
	v_mul_f32_e32 v24, v16, v36
	v_mul_f32_e32 v16, v17, v25
	v_mul_f32_e32 v22, v22, v30
	v_mul_f32_e32 v25, v16, v37
	v_mul_f32_e32 v16, v18, v26
	v_mul_f32_e32 v20, v20, v28
	v_mul_f32_e32 v21, v21, v29
	v_mul_f32_e32 v22, v22, v34
	v_mul_f32_e32 v23, v23, v31
	v_mul_f32_e32 v26, v16, v38
	v_mul_f32_e32 v16, v19, v27
	v_mul_f32_e32 v20, v20, v32
	v_mul_f32_e32 v21, v21, v33
	v_mul_f32_e32 v23, v23, v35
	v_mul_f32_e32 v19, v16, v39
	v_cvt_pk_bf16_f32 v16, v20, v21
	v_cvt_pk_bf16_f32 v17, v22, v23
	v_exp_f32_e64 v22, -v8
	v_exp_f32_e64 v23, -v9
	v_cvt_pk_bf16_f32 v18, v24, v25
	v_add_co_u32_e32 v20, vcc, s60, v52
	v_exp_f32_e64 v24, -v10
	v_cvt_pk_bf16_f32 v19, v26, v19
	s_nop 0
	v_addc_co_u32_e32 v21, vcc, 0, v53, vcc
	v_exp_f32_e64 v25, -v11
	global_store_dwordx4 v[20:21], v[16:19], off
	v_add_f32_e32 v22, 1.0, v22
	v_add_f32_e32 v23, 1.0, v23
	v_exp_f32_e64 v16, -v12
	v_exp_f32_e64 v17, -v13
	v_exp_f32_e64 v18, -v14
	v_exp_f32_e64 v19, -v15
	v_rcp_f32_e32 v22, v22
	v_add_f32_e32 v24, 1.0, v24
	v_rcp_f32_e32 v23, v23
	v_add_f32_e32 v25, 1.0, v25
	v_rcp_f32_e32 v24, v24
	v_add_f32_e32 v16, 1.0, v16
	v_add_f32_e32 v17, 1.0, v17
	v_add_f32_e32 v18, 1.0, v18
	v_add_f32_e32 v19, 1.0, v19
	v_rcp_f32_e32 v25, v25
	v_mul_f32_e32 v0, v0, v8
	v_rcp_f32_e32 v16, v16
	v_rcp_f32_e32 v17, v17
	v_rcp_f32_e32 v18, v18
	v_rcp_f32_e32 v19, v19
	v_mul_f32_e32 v8, v0, v22
	v_mul_f32_e32 v0, v1, v9
	v_mul_f32_e32 v9, v0, v23
	v_mul_f32_e32 v0, v2, v10
	v_mul_f32_e32 v10, v0, v24
	v_mul_f32_e32 v0, v3, v11
	v_mul_f32_e32 v4, v4, v12
	v_mul_f32_e32 v5, v5, v13
	v_mul_f32_e32 v6, v6, v14
	v_mul_f32_e32 v7, v7, v15
	v_mul_f32_e32 v3, v0, v25
	s_andn2_b64 vcc, exec, s[34:35]
	s_mov_b64 s[4:5], -1
	v_mul_f32_e32 v4, v4, v16
	v_mul_f32_e32 v5, v5, v17
	v_mul_f32_e32 v6, v6, v18
	v_mul_f32_e32 v7, v7, v19
	v_cvt_pk_bf16_f32 v0, v4, v5
	v_cvt_pk_bf16_f32 v1, v6, v7
	v_cvt_pk_bf16_f32 v2, v8, v9
	v_cvt_pk_bf16_f32 v3, v10, v3
	global_store_dwordx4 v[20:21], v[0:3], off offset:2048
	s_cbranch_vccnz .LBB0_292
	s_andn2_b64 vcc, exec, s[0:1]
	s_cbranch_vccnz .LBB0_291
	s_barrier
	s_branch .LBB0_291

; __device__ __forceinline__ unsigned cvt_pk_bf16(float lo, float hi) { unsigned r; asm volatile("v_cvt_pk_bf16_f32 %0, %1, %2" : "=v"(r) : "v"(lo), "v"(hi)); return r; }
; #define PG8_BAR __builtin_amdgcn_s_barrier()
;     __device__ __forceinline__ void half(const f32x4 (&acc)[2][4][2], int pm, int ai, int pn, int wr, int wc, int fr, int fq) const {
;         const int row0 = pm * BM + wr * 64 + fr, col0 = pn * HALF + wc * 32 + 8 * fq;
;         {
; #pragma unroll
;             for (int m = 0; m < 4; ++m) {
;                 float a[8], e[8];
; #pragma unroll
;                 for (int q = 0; q < 8; ++q) a[q] = acc[0][m][q >> 2][q & 3];
; #pragma unroll
;                 for (int q = 0; q < 8; ++q) e[q] = __builtin_amdgcn_exp2f(-a[q]);
; #pragma unroll
;                 for (int q = 0; q < 8; ++q) e[q] += 1.f;
; #pragma unroll
;                 for (int q = 0; q < 8; ++q) e[q] = __builtin_amdgcn_rcpf(e[q]);
; #pragma unroll
;                 for (int q = 0; q < 8; ++q) a[q] = a[q] * acc[1][m][q >> 2][q & 3] * e[q];
;                 u32x4 w; w.x = cvt_pk_bf16(a[0], a[1]); w.y = cvt_pk_bf16(a[2], a[3]); w.z = cvt_pk_bf16(a[4], a[5]); w.w = cvt_pk_bf16(a[6], a[7]);
;                 const int row = row0 + ai * HALF + m * 16;
;                 bf16_t* dst = O + (((size_t)(row >> 8) * (ldc >> 6) + (col0 >> 6)) * 256 + (row & 255)) * 64 + (col0 & 63);
;                 if (wt) asm volatile("global_store_dwordx4 %0, %1, off sc1\n\ts_nop 1" :: "v"(dst), "v"(w) : "memory"); else *(u32x4*)dst = w; }
; template <class Epi, class Sched, bool ALIGN_EPI = false, bool SP2 = false>
; __device__ __forceinline__ void gemm_phase(PG8_LAS unsigned char* lds, const Gemm g, const Sched& S, const Epi& E) {
;     ...
;         if constexpr (ALIGN_EPI) { if (wr == 0) PG8_BAR; }
.LBB0_1310:
	v_exp_f32_e64 v159, -v120
	v_exp_f32_e64 v160, -v121
	v_exp_f32_e64 v155, -v124
	v_exp_f32_e64 v156, -v125
	v_exp_f32_e64 v157, -v126
	v_exp_f32_e64 v161, -v122
	v_exp_f32_e64 v158, -v127
	v_exp_f32_e64 v162, -v123
	s_lshl_b32 s4, s60, 8
	v_add_f32_e32 v159, 1.0, v159
	s_lshl_b32 s5, s54, 7
	s_add_i32 s12, s4, s46
	v_add_f32_e32 v160, 1.0, v160
	v_rcp_f32_e32 v159, v159
	s_or_b32 s5, s5, s47
	s_ashr_i32 s12, s12, 8
	v_add_f32_e32 v155, 1.0, v155
	v_add_f32_e32 v156, 1.0, v156
	v_add_f32_e32 v157, 1.0, v157
	v_add_f32_e32 v161, 1.0, v161
	v_rcp_f32_e32 v160, v160
	s_ashr_i32 s50, s5, 6
	v_add_f32_e32 v158, 1.0, v158
	v_add_f32_e32 v162, 1.0, v162
	v_rcp_f32_e32 v155, v155
	v_rcp_f32_e32 v156, v156
	v_rcp_f32_e32 v157, v157
	v_rcp_f32_e32 v161, v161
	s_mulk_i32 s12, 0x58
	s_ashr_i32 s51, s50, 31
	v_rcp_f32_e32 v158, v158
	v_rcp_f32_e32 v162, v162
	v_mul_f32_e32 v112, v112, v120
	s_ashr_i32 s5, s12, 31
	v_mul_f32_e32 v120, v112, v159
	v_mul_f32_e32 v112, v113, v121
	s_add_u32 s12, s12, s50
	v_mul_f32_e32 v116, v116, v124
	v_mul_f32_e32 v117, v117, v125
	v_mul_f32_e32 v118, v118, v126
	v_mul_f32_e32 v121, v112, v160
	v_mul_f32_e32 v112, v114, v122
	s_addc_u32 s13, s5, s51
	v_mul_f32_e32 v116, v116, v155
	v_mul_f32_e32 v117, v117, v156
	v_mul_f32_e32 v118, v118, v157
	v_mul_f32_e32 v119, v119, v127
	v_mul_f32_e32 v122, v112, v161
	v_mul_f32_e32 v112, v115, v123
	s_lshl_b64 s[12:13], s[12:13], 15
	v_mul_f32_e32 v119, v119, v158
	v_mul_f32_e32 v115, v112, v162
	v_cvt_pk_bf16_f32 v112, v116, v117
	v_cvt_pk_bf16_f32 v113, v118, v119
	v_lshl_add_u64 v[116:117], v[138:139], 0, s[12:13]
	v_exp_f32_e64 v118, -v104
	v_lshl_add_u64 v[116:117], v[116:117], 0, v[136:137]
	v_exp_f32_e64 v119, -v105
	v_cvt_pk_bf16_f32 v114, v120, v121
	v_cvt_pk_bf16_f32 v115, v122, v115
	global_store_dwordx4 v[116:117], v[112:115], off
	v_exp_f32_e64 v120, -v106
	v_exp_f32_e64 v121, -v107
	v_exp_f32_e64 v112, -v108
	v_exp_f32_e64 v113, -v109
	v_exp_f32_e64 v114, -v110
	v_exp_f32_e64 v115, -v111
	v_add_f32_e32 v118, 1.0, v118
	v_add_f32_e32 v119, 1.0, v119
	v_rcp_f32_e32 v118, v118
	v_add_f32_e32 v112, 1.0, v112
	v_add_f32_e32 v120, 1.0, v120
	v_rcp_f32_e32 v119, v119
	v_add_f32_e32 v113, 1.0, v113
	v_add_f32_e32 v121, 1.0, v121
	v_rcp_f32_e32 v112, v112
	v_rcp_f32_e32 v120, v120
	v_add_f32_e32 v114, 1.0, v114
	v_add_f32_e32 v115, 1.0, v115
	v_rcp_f32_e32 v113, v113
	v_rcp_f32_e32 v121, v121
	v_mul_f32_e32 v96, v96, v104
	v_rcp_f32_e32 v114, v114
	v_rcp_f32_e32 v115, v115
	v_mul_f32_e32 v104, v96, v118
	v_mul_f32_e32 v96, v97, v105
	v_mul_f32_e32 v100, v100, v108
	v_mul_f32_e32 v105, v96, v119
	v_mul_f32_e32 v96, v98, v106
	v_mul_f32_e32 v100, v100, v112
	v_mul_f32_e32 v101, v101, v109
	v_mul_f32_e32 v106, v96, v120
	v_mul_f32_e32 v96, v99, v107
	v_mul_f32_e32 v101, v101, v113
	v_mul_f32_e32 v102, v102, v110
	v_mul_f32_e32 v103, v103, v111
	v_mul_f32_e32 v99, v96, v121
	v_cvt_pk_bf16_f32 v96, v100, v101
	v_exp_f32_e64 v100, -v88
	v_mul_f32_e32 v102, v102, v114
	v_mul_f32_e32 v103, v103, v115
	v_cvt_pk_bf16_f32 v97, v102, v103
	v_cvt_pk_bf16_f32 v98, v104, v105
	v_exp_f32_e64 v101, -v89
	v_cvt_pk_bf16_f32 v99, v106, v99
	global_store_dwordx4 v[116:117], v[96:99], off offset:2048
	v_exp_f32_e64 v102, -v90
	v_exp_f32_e64 v103, -v91
	v_exp_f32_e64 v96, -v92
	v_exp_f32_e64 v98, -v94
	v_exp_f32_e64 v97, -v93
	v_exp_f32_e64 v99, -v95
	v_add_f32_e32 v100, 1.0, v100
	v_add_f32_e32 v101, 1.0, v101
	v_rcp_f32_e32 v100, v100
	v_add_f32_e32 v96, 1.0, v96
	v_add_f32_e32 v98, 1.0, v98
	v_add_f32_e32 v102, 1.0, v102
	v_rcp_f32_e32 v101, v101
	v_add_f32_e32 v97, 1.0, v97
	v_add_f32_e32 v99, 1.0, v99
	v_add_f32_e32 v103, 1.0, v103
	v_rcp_f32_e32 v96, v96
	v_rcp_f32_e32 v98, v98
	v_rcp_f32_e32 v102, v102
	v_rcp_f32_e32 v97, v97
	v_rcp_f32_e32 v99, v99
	v_rcp_f32_e32 v103, v103
	v_mul_f32_e32 v80, v80, v88
	v_mul_f32_e32 v88, v80, v100
	v_mul_f32_e32 v80, v81, v89
	v_mul_f32_e32 v84, v84, v92
	v_mul_f32_e32 v86, v86, v94
	v_mul_f32_e32 v89, v80, v101
	v_mul_f32_e32 v80, v82, v90
	v_mul_f32_e32 v84, v84, v96
	v_mul_f32_e32 v85, v85, v93
	v_mul_f32_e32 v86, v86, v98
	v_mul_f32_e32 v87, v87, v95
	v_mul_f32_e32 v90, v80, v102
	v_mul_f32_e32 v80, v83, v91
	v_mul_f32_e32 v85, v85, v97
	v_mul_f32_e32 v87, v87, v99
	v_mul_f32_e32 v83, v80, v103
	v_cvt_pk_bf16_f32 v80, v84, v85
	v_cvt_pk_bf16_f32 v81, v86, v87
	v_add_co_u32_e32 v84, vcc, s62, v116
	v_exp_f32_e64 v86, -v72
	s_nop 0
	v_addc_co_u32_e32 v85, vcc, 0, v117, vcc
	v_exp_f32_e64 v87, -v73
	v_cvt_pk_bf16_f32 v82, v88, v89
	v_cvt_pk_bf16_f32 v83, v90, v83
	global_store_dwordx4 v[84:85], v[80:83], off
	v_exp_f32_e64 v88, -v74
	v_exp_f32_e64 v89, -v75
	v_exp_f32_e64 v81, -v77
	v_exp_f32_e64 v80, -v76
	v_exp_f32_e64 v82, -v78
	v_exp_f32_e64 v83, -v79
	v_add_f32_e32 v86, 1.0, v86
	v_add_f32_e32 v87, 1.0, v87
	v_rcp_f32_e32 v86, v86
	v_add_f32_e32 v81, 1.0, v81
	v_add_f32_e32 v88, 1.0, v88
	v_rcp_f32_e32 v87, v87
	v_add_f32_e32 v80, 1.0, v80
	v_add_f32_e32 v82, 1.0, v82
	v_add_f32_e32 v89, 1.0, v89
	v_rcp_f32_e32 v81, v81
	v_rcp_f32_e32 v88, v88
	v_add_f32_e32 v83, 1.0, v83
	v_rcp_f32_e32 v80, v80
	v_rcp_f32_e32 v82, v82
	v_rcp_f32_e32 v89, v89
	v_mul_f32_e32 v64, v64, v72
	v_rcp_f32_e32 v83, v83
	v_mul_f32_e32 v72, v64, v86
	v_mul_f32_e32 v64, v65, v73
	v_mul_f32_e32 v69, v69, v77
	v_mul_f32_e32 v73, v64, v87
	v_mul_f32_e32 v64, v66, v74
	v_mul_f32_e32 v68, v68, v76
	v_mul_f32_e32 v69, v69, v81
	v_mul_f32_e32 v70, v70, v78
	v_mul_f32_e32 v74, v64, v88
	v_mul_f32_e32 v64, v67, v75
	v_mul_f32_e32 v68, v68, v80
	v_mul_f32_e32 v70, v70, v82
	v_mul_f32_e32 v71, v71, v79
	v_mul_f32_e32 v67, v64, v89
	v_cvt_pk_bf16_f32 v64, v68, v69
	v_exp_f32_e64 v69, -v56
	v_mul_f32_e32 v71, v71, v83
	v_cvt_pk_bf16_f32 v65, v70, v71
	v_exp_f32_e64 v70, -v57
	v_cvt_pk_bf16_f32 v66, v72, v73
	v_cvt_pk_bf16_f32 v67, v74, v67
	global_store_dwordx4 v[84:85], v[64:67], off offset:2048
	s_and_b64 vcc, exec, s[34:35]
	s_cbranch_vccz .Lepi_1310
	s_barrier
; __device__ __forceinline__ unsigned cvt_pk_bf16(float lo, float hi) { unsigned r; asm volatile("v_cvt_pk_bf16_f32 %0, %1, %2" : "=v"(r) : "v"(lo), "v"(hi)); return r; }
; #define PG8_BAR __builtin_amdgcn_s_barrier()
;     __device__ __forceinline__ void half(const f32x4 (&acc)[2][4][2], int pm, int ai, int pn, int wr, int wc, int fr, int fq) const {
;         const int row0 = pm * BM + wr * 64 + fr, col0 = pn * HALF + wc * 32 + 8 * fq;
;         {
; #pragma unroll
;             for (int m = 0; m < 4; ++m) {
;                 float a[8], e[8];
; #pragma unroll
;                 for (int q = 0; q < 8; ++q) a[q] = acc[0][m][q >> 2][q & 3];
; #pragma unroll
;                 for (int q = 0; q < 8; ++q) e[q] = __builtin_amdgcn_exp2f(-a[q]);
; #pragma unroll
;                 for (int q = 0; q < 8; ++q) e[q] += 1.f;
; #pragma unroll
;                 for (int q = 0; q < 8; ++q) e[q] = __builtin_amdgcn_rcpf(e[q]);
; #pragma unroll
;                 for (int q = 0; q < 8; ++q) a[q] = a[q] * acc[1][m][q >> 2][q & 3] * e[q];
;                 u32x4 w; w.x = cvt_pk_bf16(a[0], a[1]); w.y = cvt_pk_bf16(a[2], a[3]); w.z = cvt_pk_bf16(a[4], a[5]); w.w = cvt_pk_bf16(a[6], a[7]);
;                 const int row = row0 + ai * HALF + m * 16;
;                 bf16_t* dst = O + (((size_t)(row >> 8) * (ldc >> 6) + (col0 >> 6)) * 256 + (row & 255)) * 64 + (col0 & 63);
;                 if (wt) asm volatile("global_store_dwordx4 %0, %1, off sc1\n\ts_nop 1" :: "v"(dst), "v"(w) : "memory"); else *(u32x4*)dst = w; }
;         }
; template <class Epi, class Sched, bool ALIGN_EPI = false, bool SP2 = false>
; __device__ __forceinline__ void gemm_phase(PG8_LAS unsigned char* lds, const Gemm g, const Sched& S, const Epi& E) {
;     ...
;         if (!has_next) break;
; #pragma unroll
;         for (int a = 0; a < 2; ++a)
; #pragma unroll
;             for (int b = 0; b < 2; ++b)
; #pragma unroll
;                 for (int m = 0; m < 4; ++m)
; #pragma unroll
;                     for (int n = 0; n < 2; ++n) acc[a][b][m][n] = (f32x4){0.f, 0.f, 0.f, 0.f};
;         cur = nxt; cA = nA; cB = nB; ++ui;
;         if constexpr (ALIGN_EPI) { if (wr == 1) PG8_BAR; }
.Lepi_1310:
	v_exp_f32_e64 v71, -v58
	v_exp_f32_e64 v72, -v59
	v_exp_f32_e64 v65, -v60
	v_exp_f32_e64 v66, -v61
	v_add_f32_e32 v69, 1.0, v69
	v_add_f32_e32 v70, 1.0, v70
	v_rcp_f32_e32 v69, v69
	v_exp_f32_e64 v67, -v62
	v_add_f32_e32 v65, 1.0, v65
	v_add_f32_e32 v71, 1.0, v71
	v_rcp_f32_e32 v70, v70
	v_exp_f32_e64 v68, -v63
	v_add_f32_e32 v66, 1.0, v66
	v_add_f32_e32 v72, 1.0, v72
	v_rcp_f32_e32 v65, v65
	v_rcp_f32_e32 v71, v71
	v_rcp_f32_e32 v66, v66
	v_rcp_f32_e32 v72, v72
	v_mul_f32_e32 v48, v48, v56
	v_mul_f32_e32 v56, v48, v69
	v_mul_f32_e32 v48, v49, v57
	v_add_u32_e32 v64, s4, v151
	v_add_f32_e32 v67, 1.0, v67
	v_mul_f32_e32 v52, v52, v60
	v_mul_f32_e32 v57, v48, v70
	v_mul_f32_e32 v48, v50, v58
	v_lshrrev_b32_e32 v64, 8, v64
	v_add_f32_e32 v68, 1.0, v68
	v_rcp_f32_e32 v67, v67
	v_mul_f32_e32 v52, v52, v65
	v_mul_f32_e32 v53, v53, v61
	v_mul_f32_e32 v58, v48, v71
	v_mul_f32_e32 v48, v51, v59
	v_rcp_f32_e32 v68, v68
	v_mul_f32_e32 v53, v53, v66
	v_mul_f32_e32 v51, v48, v72
	v_cvt_pk_bf16_f32 v48, v52, v53
	v_mul_i32_i24_e32 v52, 0x58, v64
	v_ashrrev_i32_e32 v53, 31, v52
	v_mul_f32_e32 v54, v54, v62
	v_lshl_add_u64 v[52:53], v[52:53], 0, s[50:51]
	v_mul_f32_e32 v54, v54, v67
	v_mul_f32_e32 v55, v55, v63
	v_lshlrev_b64 v[52:53], 15, v[52:53]
	v_mul_f32_e32 v55, v55, v68
	v_cvt_pk_bf16_f32 v49, v54, v55
	v_lshl_add_u64 v[52:53], v[140:141], 0, v[52:53]
	v_exp_f32_e64 v54, -v40
	v_lshl_add_u64 v[52:53], v[52:53], 0, v[136:137]
	v_exp_f32_e64 v55, -v41
	v_cvt_pk_bf16_f32 v50, v56, v57
	v_cvt_pk_bf16_f32 v51, v58, v51
	global_store_dwordx4 v[52:53], v[48:51], off
	v_exp_f32_e64 v56, -v42
	v_exp_f32_e64 v57, -v43
	v_exp_f32_e64 v48, -v44
	v_exp_f32_e64 v49, -v45
	v_exp_f32_e64 v50, -v46
	v_exp_f32_e64 v51, -v47
	v_add_f32_e32 v54, 1.0, v54
	v_add_f32_e32 v55, 1.0, v55
	v_rcp_f32_e32 v54, v54
	v_add_f32_e32 v48, 1.0, v48
	v_add_f32_e32 v56, 1.0, v56
	v_rcp_f32_e32 v55, v55
	v_add_f32_e32 v49, 1.0, v49
	v_add_f32_e32 v57, 1.0, v57
	v_rcp_f32_e32 v48, v48
	v_rcp_f32_e32 v56, v56
	v_add_f32_e32 v50, 1.0, v50
	v_add_f32_e32 v51, 1.0, v51
	v_rcp_f32_e32 v49, v49
	v_rcp_f32_e32 v57, v57
	v_mul_f32_e32 v32, v32, v40
	v_rcp_f32_e32 v50, v50
	v_rcp_f32_e32 v51, v51
	v_mul_f32_e32 v40, v32, v54
	v_mul_f32_e32 v32, v33, v41
	v_mul_f32_e32 v36, v36, v44
	v_mul_f32_e32 v41, v32, v55
	v_mul_f32_e32 v32, v34, v42
	v_mul_f32_e32 v36, v36, v48
	v_mul_f32_e32 v37, v37, v45
	v_mul_f32_e32 v42, v32, v56
	v_mul_f32_e32 v32, v35, v43
	v_mul_f32_e32 v37, v37, v49
	v_mul_f32_e32 v38, v38, v46
	v_mul_f32_e32 v39, v39, v47
	v_mul_f32_e32 v35, v32, v57
	v_cvt_pk_bf16_f32 v32, v36, v37
	v_exp_f32_e64 v36, -v24
	v_mul_f32_e32 v38, v38, v50
	v_mul_f32_e32 v39, v39, v51
	v_cvt_pk_bf16_f32 v33, v38, v39
	v_cvt_pk_bf16_f32 v34, v40, v41
	v_exp_f32_e64 v37, -v25
	v_cvt_pk_bf16_f32 v35, v42, v35
	global_store_dwordx4 v[52:53], v[32:35], off offset:2048
	v_exp_f32_e64 v38, -v26
	v_exp_f32_e64 v39, -v27
	v_exp_f32_e64 v34, -v30
	v_exp_f32_e64 v32, -v28
	v_exp_f32_e64 v33, -v29
	v_exp_f32_e64 v35, -v31
	v_add_f32_e32 v36, 1.0, v36
	v_add_f32_e32 v37, 1.0, v37
	v_rcp_f32_e32 v36, v36
	v_add_f32_e32 v34, 1.0, v34
	v_add_f32_e32 v38, 1.0, v38
	v_rcp_f32_e32 v37, v37
	v_add_f32_e32 v32, 1.0, v32
	v_add_f32_e32 v33, 1.0, v33
	v_add_f32_e32 v35, 1.0, v35
	v_add_f32_e32 v39, 1.0, v39
	v_rcp_f32_e32 v34, v34
	v_rcp_f32_e32 v38, v38
	v_rcp_f32_e32 v32, v32
	v_rcp_f32_e32 v33, v33
	v_rcp_f32_e32 v35, v35
	v_rcp_f32_e32 v39, v39
	v_mul_f32_e32 v16, v16, v24
	v_mul_f32_e32 v24, v16, v36
	v_mul_f32_e32 v16, v17, v25
	v_mul_f32_e32 v22, v22, v30
	v_mul_f32_e32 v25, v16, v37
	v_mul_f32_e32 v16, v18, v26
	v_mul_f32_e32 v20, v20, v28
	v_mul_f32_e32 v21, v21, v29
	v_mul_f32_e32 v22, v22, v34
	v_mul_f32_e32 v23, v23, v31
	v_mul_f32_e32 v26, v16, v38
	v_mul_f32_e32 v16, v19, v27
	v_mul_f32_e32 v20, v20, v32
	v_mul_f32_e32 v21, v21, v33
	v_mul_f32_e32 v23, v23, v35
	v_mul_f32_e32 v19, v16, v39
	v_cvt_pk_bf16_f32 v16, v20, v21
	v_cvt_pk_bf16_f32 v17, v22, v23
	v_exp_f32_e64 v22, -v8
	v_exp_f32_e64 v23, -v9
	v_cvt_pk_bf16_f32 v18, v24, v25
	v_add_co_u32_e32 v20, vcc, s62, v52
	v_exp_f32_e64 v24, -v10
	v_cvt_pk_bf16_f32 v19, v26, v19
	s_nop 0
	v_addc_co_u32_e32 v21, vcc, 0, v53, vcc
	v_exp_f32_e64 v25, -v11
	global_store_dwordx4 v[20:21], v[16:19], off
	v_add_f32_e32 v22, 1.0, v22
	v_add_f32_e32 v23, 1.0, v23
	v_exp_f32_e64 v16, -v12
	v_exp_f32_e64 v17, -v13
	v_exp_f32_e64 v18, -v14
	v_exp_f32_e64 v19, -v15
	v_rcp_f32_e32 v22, v22
	v_add_f32_e32 v24, 1.0, v24
	v_rcp_f32_e32 v23, v23
	v_add_f32_e32 v25, 1.0, v25
	v_rcp_f32_e32 v24, v24
	v_add_f32_e32 v16, 1.0, v16
	v_add_f32_e32 v17, 1.0, v17
	v_add_f32_e32 v18, 1.0, v18
	v_add_f32_e32 v19, 1.0, v19
	v_rcp_f32_e32 v25, v25
	v_mul_f32_e32 v0, v0, v8
	v_rcp_f32_e32 v16, v16
	v_rcp_f32_e32 v17, v17
	v_rcp_f32_e32 v18, v18
	v_rcp_f32_e32 v19, v19
	v_mul_f32_e32 v8, v0, v22
	v_mul_f32_e32 v0, v1, v9
	v_mul_f32_e32 v9, v0, v23
	v_mul_f32_e32 v0, v2, v10
	v_mul_f32_e32 v10, v0, v24
	v_mul_f32_e32 v0, v3, v11
	v_mul_f32_e32 v4, v4, v12
	v_mul_f32_e32 v5, v5, v13
	v_mul_f32_e32 v6, v6, v14
	v_mul_f32_e32 v7, v7, v15
	v_mul_f32_e32 v3, v0, v25
	s_andn2_b64 vcc, exec, s[42:43]
	s_mov_b64 s[4:5], -1
	v_mul_f32_e32 v4, v4, v16
	v_mul_f32_e32 v5, v5, v17
	v_mul_f32_e32 v6, v6, v18
	v_mul_f32_e32 v7, v7, v19
	v_cvt_pk_bf16_f32 v0, v4, v5
	v_cvt_pk_bf16_f32 v1, v6, v7
	v_cvt_pk_bf16_f32 v2, v8, v9
	v_cvt_pk_bf16_f32 v3, v10, v3
	global_store_dwordx4 v[20:21], v[0:3], off offset:2048
	s_cbranch_vccnz .LBB0_1299
	s_andn2_b64 vcc, exec, s[0:1]
	s_cbranch_vccnz .LBB0_1298
	s_barrier
	s_branch .LBB0_1298

; __device__ __forceinline__ unsigned cvt_pk_bf16(float lo, float hi) { unsigned r; asm volatile("v_cvt_pk_bf16_f32 %0, %1, %2" : "=v"(r) : "v"(lo), "v"(hi)); return r; }
; #define PG8_BAR __builtin_amdgcn_s_barrier()
;     __device__ __forceinline__ void half(const f32x4 (&acc)[2][4][2], int pm, int ai, int pn, int wr, int wc, int fr, int fq) const {
;         const int row0 = pm * BM + wr * 64 + fr, col0 = pn * HALF + wc * 32 + 8 * fq;
;         {
; #pragma unroll
;             for (int m = 0; m < 4; ++m) {
;                 float a[8], e[8];
; #pragma unroll
;                 for (int q = 0; q < 8; ++q) a[q] = acc[0][m][q >> 2][q & 3];
; #pragma unroll
;                 for (int q = 0; q < 8; ++q) e[q] = __builtin_amdgcn_exp2f(-a[q]);
; #pragma unroll
;                 for (int q = 0; q < 8; ++q) e[q] += 1.f;
; #pragma unroll
;                 for (int q = 0; q < 8; ++q) e[q] = __builtin_amdgcn_rcpf(e[q]);
; #pragma unroll
;                 for (int q = 0; q < 8; ++q) a[q] = a[q] * acc[1][m][q >> 2][q & 3] * e[q];
;                 u32x4 w; w.x = cvt_pk_bf16(a[0], a[1]); w.y = cvt_pk_bf16(a[2], a[3]); w.z = cvt_pk_bf16(a[4], a[5]); w.w = cvt_pk_bf16(a[6], a[7]);
;                 const int row = row0 + ai * HALF + m * 16;
;                 bf16_t* dst = O + (((size_t)(row >> 8) * (ldc >> 6) + (col0 >> 6)) * 256 + (row & 255)) * 64 + (col0 & 63);
;                 if (wt) asm volatile("global_store_dwordx4 %0, %1, off sc1\n\ts_nop 1" :: "v"(dst), "v"(w) : "memory"); else *(u32x4*)dst = w; }
;         }
; template <class Epi, class Sched, bool ALIGN_EPI = false, bool SP2 = false>
; __device__ __forceinline__ void gemm_phase(PG8_LAS unsigned char* lds, const Gemm g, const Sched& S, const Epi& E) {
;     ...
;         if constexpr (ALIGN_EPI) { if (wr == 0) PG8_BAR; }
;         if constexpr (!Epi::AFTER_DRAIN) { E(acc, cur, wr, wc, fr, fq); S.done(cur); }
.LBB0_1660:
	v_exp_f32_e64 v159, -v120
	v_exp_f32_e64 v160, -v121
	v_exp_f32_e64 v155, -v124
	v_exp_f32_e64 v156, -v125
	v_exp_f32_e64 v157, -v126
	v_exp_f32_e64 v161, -v122
	v_exp_f32_e64 v158, -v127
	v_exp_f32_e64 v162, -v123
	s_lshl_b32 s4, s62, 8
	v_add_f32_e32 v159, 1.0, v159
	s_lshl_b32 s5, s60, 7
	s_add_i32 s12, s4, s42
	v_add_f32_e32 v160, 1.0, v160
	v_rcp_f32_e32 v159, v159
	s_or_b32 s5, s5, s43
	s_ashr_i32 s12, s12, 8
	v_add_f32_e32 v155, 1.0, v155
	v_add_f32_e32 v156, 1.0, v156
	v_add_f32_e32 v157, 1.0, v157
	v_add_f32_e32 v161, 1.0, v161
	v_rcp_f32_e32 v160, v160
	s_ashr_i32 s50, s5, 6
	v_add_f32_e32 v158, 1.0, v158
	v_add_f32_e32 v162, 1.0, v162
	v_rcp_f32_e32 v155, v155
	v_rcp_f32_e32 v156, v156
	v_rcp_f32_e32 v157, v157
	v_rcp_f32_e32 v161, v161
	s_mulk_i32 s12, 0x58
	s_ashr_i32 s51, s50, 31
	v_rcp_f32_e32 v158, v158
	v_rcp_f32_e32 v162, v162
	v_mul_f32_e32 v112, v112, v120
	s_ashr_i32 s5, s12, 31
	v_mul_f32_e32 v120, v112, v159
	v_mul_f32_e32 v112, v113, v121
	s_add_u32 s12, s12, s50
	v_mul_f32_e32 v116, v116, v124
	v_mul_f32_e32 v117, v117, v125
	v_mul_f32_e32 v118, v118, v126
	v_mul_f32_e32 v121, v112, v160
	v_mul_f32_e32 v112, v114, v122
	s_addc_u32 s13, s5, s51
	v_mul_f32_e32 v116, v116, v155
	v_mul_f32_e32 v117, v117, v156
	v_mul_f32_e32 v118, v118, v157
	v_mul_f32_e32 v119, v119, v127
	v_mul_f32_e32 v122, v112, v161
	v_mul_f32_e32 v112, v115, v123
	s_lshl_b64 s[12:13], s[12:13], 15
	v_mul_f32_e32 v119, v119, v158
	v_mul_f32_e32 v115, v112, v162
	v_cvt_pk_bf16_f32 v112, v116, v117
	v_cvt_pk_bf16_f32 v113, v118, v119
	v_lshl_add_u64 v[116:117], v[138:139], 0, s[12:13]
	v_exp_f32_e64 v118, -v104
	v_lshl_add_u64 v[116:117], v[116:117], 0, v[136:137]
	v_exp_f32_e64 v119, -v105
	v_cvt_pk_bf16_f32 v114, v120, v121
	v_cvt_pk_bf16_f32 v115, v122, v115
	global_store_dwordx4 v[116:117], v[112:115], off
	v_exp_f32_e64 v120, -v106
	v_exp_f32_e64 v121, -v107
	v_exp_f32_e64 v112, -v108
	v_exp_f32_e64 v113, -v109
	v_exp_f32_e64 v114, -v110
	v_exp_f32_e64 v115, -v111
	v_add_f32_e32 v118, 1.0, v118
	v_add_f32_e32 v119, 1.0, v119
	v_rcp_f32_e32 v118, v118
	v_add_f32_e32 v112, 1.0, v112
	v_add_f32_e32 v120, 1.0, v120
	v_rcp_f32_e32 v119, v119
	v_add_f32_e32 v113, 1.0, v113
	v_add_f32_e32 v121, 1.0, v121
	v_rcp_f32_e32 v112, v112
	v_rcp_f32_e32 v120, v120
	v_add_f32_e32 v114, 1.0, v114
	v_add_f32_e32 v115, 1.0, v115
	v_rcp_f32_e32 v113, v113
	v_rcp_f32_e32 v121, v121
	v_mul_f32_e32 v96, v96, v104
	v_rcp_f32_e32 v114, v114
	v_rcp_f32_e32 v115, v115
	v_mul_f32_e32 v104, v96, v118
	v_mul_f32_e32 v96, v97, v105
	v_mul_f32_e32 v100, v100, v108
	v_mul_f32_e32 v105, v96, v119
	v_mul_f32_e32 v96, v98, v106
	v_mul_f32_e32 v100, v100, v112
	v_mul_f32_e32 v101, v101, v109
	v_mul_f32_e32 v106, v96, v120
	v_mul_f32_e32 v96, v99, v107
	v_mul_f32_e32 v101, v101, v113
	v_mul_f32_e32 v102, v102, v110
	v_mul_f32_e32 v103, v103, v111
	v_mul_f32_e32 v99, v96, v121
	v_cvt_pk_bf16_f32 v96, v100, v101
	v_exp_f32_e64 v100, -v88
	v_mul_f32_e32 v102, v102, v114
	v_mul_f32_e32 v103, v103, v115
	v_cvt_pk_bf16_f32 v97, v102, v103
	v_cvt_pk_bf16_f32 v98, v104, v105
	v_exp_f32_e64 v101, -v89
	v_cvt_pk_bf16_f32 v99, v106, v99
	global_store_dwordx4 v[116:117], v[96:99], off offset:2048
	v_exp_f32_e64 v102, -v90
	v_exp_f32_e64 v103, -v91
	v_exp_f32_e64 v96, -v92
	v_exp_f32_e64 v98, -v94
	v_exp_f32_e64 v97, -v93
	v_exp_f32_e64 v99, -v95
	v_add_f32_e32 v100, 1.0, v100
	v_add_f32_e32 v101, 1.0, v101
	v_rcp_f32_e32 v100, v100
	v_add_f32_e32 v96, 1.0, v96
	v_add_f32_e32 v98, 1.0, v98
	v_add_f32_e32 v102, 1.0, v102
	v_rcp_f32_e32 v101, v101
	v_add_f32_e32 v97, 1.0, v97
	v_add_f32_e32 v99, 1.0, v99
	v_add_f32_e32 v103, 1.0, v103
	v_rcp_f32_e32 v96, v96
	v_rcp_f32_e32 v98, v98
	v_rcp_f32_e32 v102, v102
	v_rcp_f32_e32 v97, v97
	v_rcp_f32_e32 v99, v99
	v_rcp_f32_e32 v103, v103
	v_mul_f32_e32 v80, v80, v88
	v_mul_f32_e32 v88, v80, v100
	v_mul_f32_e32 v80, v81, v89
	v_mul_f32_e32 v84, v84, v92
	v_mul_f32_e32 v86, v86, v94
	v_mul_f32_e32 v89, v80, v101
	v_mul_f32_e32 v80, v82, v90
	v_mul_f32_e32 v84, v84, v96
	v_mul_f32_e32 v85, v85, v93
	v_mul_f32_e32 v86, v86, v98
	v_mul_f32_e32 v87, v87, v95
	v_mul_f32_e32 v90, v80, v102
	v_mul_f32_e32 v80, v83, v91
	v_mul_f32_e32 v85, v85, v97
	v_mul_f32_e32 v87, v87, v99
	v_mul_f32_e32 v83, v80, v103
	v_cvt_pk_bf16_f32 v80, v84, v85
	v_cvt_pk_bf16_f32 v81, v86, v87
	v_add_co_u32_e32 v84, vcc, s61, v116
	v_exp_f32_e64 v86, -v72
	s_nop 0
	v_addc_co_u32_e32 v85, vcc, 0, v117, vcc
	v_exp_f32_e64 v87, -v73
	v_cvt_pk_bf16_f32 v82, v88, v89
	v_cvt_pk_bf16_f32 v83, v90, v83
	global_store_dwordx4 v[84:85], v[80:83], off
	v_exp_f32_e64 v88, -v74
	v_exp_f32_e64 v89, -v75
	v_exp_f32_e64 v81, -v77
	v_exp_f32_e64 v80, -v76
	v_exp_f32_e64 v82, -v78
	v_exp_f32_e64 v83, -v79
	v_add_f32_e32 v86, 1.0, v86
	v_add_f32_e32 v87, 1.0, v87
	v_rcp_f32_e32 v86, v86
	v_add_f32_e32 v81, 1.0, v81
	v_add_f32_e32 v88, 1.0, v88
	v_rcp_f32_e32 v87, v87
	v_add_f32_e32 v80, 1.0, v80
	v_add_f32_e32 v82, 1.0, v82
	v_add_f32_e32 v89, 1.0, v89
	v_rcp_f32_e32 v81, v81
	v_rcp_f32_e32 v88, v88
	v_add_f32_e32 v83, 1.0, v83
	v_rcp_f32_e32 v80, v80
	v_rcp_f32_e32 v82, v82
	v_rcp_f32_e32 v89, v89
	v_mul_f32_e32 v64, v64, v72
	v_rcp_f32_e32 v83, v83
	v_mul_f32_e32 v72, v64, v86
	v_mul_f32_e32 v64, v65, v73
	v_mul_f32_e32 v69, v69, v77
	v_mul_f32_e32 v73, v64, v87
	v_mul_f32_e32 v64, v66, v74
	v_mul_f32_e32 v68, v68, v76
	v_mul_f32_e32 v69, v69, v81
	v_mul_f32_e32 v70, v70, v78
	v_mul_f32_e32 v74, v64, v88
	v_mul_f32_e32 v64, v67, v75
	v_mul_f32_e32 v68, v68, v80
	v_mul_f32_e32 v70, v70, v82
	v_mul_f32_e32 v71, v71, v79
	v_mul_f32_e32 v67, v64, v89
	v_cvt_pk_bf16_f32 v64, v68, v69
	v_exp_f32_e64 v69, -v56
	v_mul_f32_e32 v71, v71, v83
	v_cvt_pk_bf16_f32 v65, v70, v71
	v_exp_f32_e64 v70, -v57
	v_cvt_pk_bf16_f32 v66, v72, v73
	v_cvt_pk_bf16_f32 v67, v74, v67
	global_store_dwordx4 v[84:85], v[64:67], off offset:2048
	s_and_b64 vcc, exec, s[34:35]
	s_cbranch_vccz .Lepi_1660
	s_barrier
; __device__ __forceinline__ unsigned cvt_pk_bf16(float lo, float hi) { unsigned r; asm volatile("v_cvt_pk_bf16_f32 %0, %1, %2" : "=v"(r) : "v"(lo), "v"(hi)); return r; }
; #define PG8_BAR __builtin_amdgcn_s_barrier()
;     __device__ __forceinline__ void half(const f32x4 (&acc)[2][4][2], int pm, int ai, int pn, int wr, int wc, int fr, int fq) const {
;         const int row0 = pm * BM + wr * 64 + fr, col0 = pn * HALF + wc * 32 + 8 * fq;
;         {
; #pragma unroll
;             for (int m = 0; m < 4; ++m) {
;                 float a[8], e[8];
; #pragma unroll
;                 for (int q = 0; q < 8; ++q) a[q] = acc[0][m][q >> 2][q & 3];
; #pragma unroll
;                 for (int q = 0; q < 8; ++q) e[q] = __builtin_amdgcn_exp2f(-a[q]);
; #pragma unroll
;                 for (int q = 0; q < 8; ++q) e[q] += 1.f;
; #pragma unroll
;                 for (int q = 0; q < 8; ++q) e[q] = __builtin_amdgcn_rcpf(e[q]);
; #pragma unroll
;                 for (int q = 0; q < 8; ++q) a[q] = a[q] * acc[1][m][q >> 2][q & 3] * e[q];
;                 u32x4 w; w.x = cvt_pk_bf16(a[0], a[1]); w.y = cvt_pk_bf16(a[2], a[3]); w.z = cvt_pk_bf16(a[4], a[5]); w.w = cvt_pk_bf16(a[6], a[7]);
;                 const int row = row0 + ai * HALF + m * 16;
;                 bf16_t* dst = O + (((size_t)(row >> 8) * (ldc >> 6) + (col0 >> 6)) * 256 + (row & 255)) * 64 + (col0 & 63);
;                 if (wt) asm volatile("global_store_dwordx4 %0, %1, off sc1\n\ts_nop 1" :: "v"(dst), "v"(w) : "memory"); else *(u32x4*)dst = w; }
;         }
; template <class Epi, class Sched, bool ALIGN_EPI = false, bool SP2 = false>
; __device__ __forceinline__ void gemm_phase(PG8_LAS unsigned char* lds, const Gemm g, const Sched& S, const Epi& E) {
;     ...
;         if (!has_next) break;
; #pragma unroll
;         for (int a = 0; a < 2; ++a)
; #pragma unroll
;             for (int b = 0; b < 2; ++b)
; #pragma unroll
;                 for (int m = 0; m < 4; ++m)
; #pragma unroll
;                     for (int n = 0; n < 2; ++n) acc[a][b][m][n] = (f32x4){0.f, 0.f, 0.f, 0.f};
;         cur = nxt; cA = nA; cB = nB; ++ui;
;         if constexpr (ALIGN_EPI) { if (wr == 1) PG8_BAR; }
.Lepi_1660:
	v_exp_f32_e64 v71, -v58
	v_exp_f32_e64 v72, -v59
	v_exp_f32_e64 v65, -v60
	v_exp_f32_e64 v66, -v61
	v_add_f32_e32 v69, 1.0, v69
	v_add_f32_e32 v70, 1.0, v70
	v_rcp_f32_e32 v69, v69
	v_exp_f32_e64 v67, -v62
	v_add_f32_e32 v65, 1.0, v65
	v_add_f32_e32 v71, 1.0, v71
	v_rcp_f32_e32 v70, v70
	v_exp_f32_e64 v68, -v63
	v_add_f32_e32 v66, 1.0, v66
	v_add_f32_e32 v72, 1.0, v72
	v_rcp_f32_e32 v65, v65
	v_rcp_f32_e32 v71, v71
	v_rcp_f32_e32 v66, v66
	v_rcp_f32_e32 v72, v72
	v_mul_f32_e32 v48, v48, v56
	v_mul_f32_e32 v56, v48, v69
	v_mul_f32_e32 v48, v49, v57
	v_add_u32_e32 v64, s4, v151
	v_add_f32_e32 v67, 1.0, v67
	v_mul_f32_e32 v52, v52, v60
	v_mul_f32_e32 v57, v48, v70
	v_mul_f32_e32 v48, v50, v58
	v_lshrrev_b32_e32 v64, 8, v64
	v_add_f32_e32 v68, 1.0, v68
	v_rcp_f32_e32 v67, v67
	v_mul_f32_e32 v52, v52, v65
	v_mul_f32_e32 v53, v53, v61
	v_mul_f32_e32 v58, v48, v71
	v_mul_f32_e32 v48, v51, v59
	v_rcp_f32_e32 v68, v68
	v_mul_f32_e32 v53, v53, v66
	v_mul_f32_e32 v51, v48, v72
	v_cvt_pk_bf16_f32 v48, v52, v53
	v_mul_i32_i24_e32 v52, 0x58, v64
	v_ashrrev_i32_e32 v53, 31, v52
	v_mul_f32_e32 v54, v54, v62
	v_lshl_add_u64 v[52:53], v[52:53], 0, s[50:51]
	v_mul_f32_e32 v54, v54, v67
	v_mul_f32_e32 v55, v55, v63
	v_lshlrev_b64 v[52:53], 15, v[52:53]
	v_mul_f32_e32 v55, v55, v68
	v_cvt_pk_bf16_f32 v49, v54, v55
	v_lshl_add_u64 v[52:53], v[140:141], 0, v[52:53]
	v_exp_f32_e64 v54, -v40
	v_lshl_add_u64 v[52:53], v[52:53], 0, v[136:137]
	v_exp_f32_e64 v55, -v41
	v_cvt_pk_bf16_f32 v50, v56, v57
	v_cvt_pk_bf16_f32 v51, v58, v51
	global_store_dwordx4 v[52:53], v[48:51], off
	v_exp_f32_e64 v56, -v42
	v_exp_f32_e64 v57, -v43
	v_exp_f32_e64 v48, -v44
	v_exp_f32_e64 v49, -v45
	v_exp_f32_e64 v50, -v46
	v_exp_f32_e64 v51, -v47
	v_add_f32_e32 v54, 1.0, v54
	v_add_f32_e32 v55, 1.0, v55
	v_rcp_f32_e32 v54, v54
	v_add_f32_e32 v48, 1.0, v48
	v_add_f32_e32 v56, 1.0, v56
	v_rcp_f32_e32 v55, v55
	v_add_f32_e32 v49, 1.0, v49
	v_add_f32_e32 v57, 1.0, v57
	v_rcp_f32_e32 v48, v48
	v_rcp_f32_e32 v56, v56
	v_add_f32_e32 v50, 1.0, v50
	v_add_f32_e32 v51, 1.0, v51
	v_rcp_f32_e32 v49, v49
	v_rcp_f32_e32 v57, v57
	v_mul_f32_e32 v32, v32, v40
	v_rcp_f32_e32 v50, v50
	v_rcp_f32_e32 v51, v51
	v_mul_f32_e32 v40, v32, v54
	v_mul_f32_e32 v32, v33, v41
	v_mul_f32_e32 v36, v36, v44
	v_mul_f32_e32 v41, v32, v55
	v_mul_f32_e32 v32, v34, v42
	v_mul_f32_e32 v36, v36, v48
	v_mul_f32_e32 v37, v37, v45
	v_mul_f32_e32 v42, v32, v56
	v_mul_f32_e32 v32, v35, v43
	v_mul_f32_e32 v37, v37, v49
	v_mul_f32_e32 v38, v38, v46
	v_mul_f32_e32 v39, v39, v47
	v_mul_f32_e32 v35, v32, v57
	v_cvt_pk_bf16_f32 v32, v36, v37
	v_exp_f32_e64 v36, -v24
	v_mul_f32_e32 v38, v38, v50
	v_mul_f32_e32 v39, v39, v51
	v_cvt_pk_bf16_f32 v33, v38, v39
	v_cvt_pk_bf16_f32 v34, v40, v41
	v_exp_f32_e64 v37, -v25
	v_cvt_pk_bf16_f32 v35, v42, v35
	global_store_dwordx4 v[52:53], v[32:35], off offset:2048
	v_exp_f32_e64 v38, -v26
	v_exp_f32_e64 v39, -v27
	v_exp_f32_e64 v34, -v30
	v_exp_f32_e64 v32, -v28
	v_exp_f32_e64 v33, -v29
	v_exp_f32_e64 v35, -v31
	v_add_f32_e32 v36, 1.0, v36
	v_add_f32_e32 v37, 1.0, v37
	v_rcp_f32_e32 v36, v36
	v_add_f32_e32 v34, 1.0, v34
	v_add_f32_e32 v38, 1.0, v38
	v_rcp_f32_e32 v37, v37
	v_add_f32_e32 v32, 1.0, v32
	v_add_f32_e32 v33, 1.0, v33
	v_add_f32_e32 v35, 1.0, v35
	v_add_f32_e32 v39, 1.0, v39
	v_rcp_f32_e32 v34, v34
	v_rcp_f32_e32 v38, v38
	v_rcp_f32_e32 v32, v32
	v_rcp_f32_e32 v33, v33
	v_rcp_f32_e32 v35, v35
	v_rcp_f32_e32 v39, v39
	v_mul_f32_e32 v16, v16, v24
	v_mul_f32_e32 v24, v16, v36
	v_mul_f32_e32 v16, v17, v25
	v_mul_f32_e32 v22, v22, v30
	v_mul_f32_e32 v25, v16, v37
	v_mul_f32_e32 v16, v18, v26
	v_mul_f32_e32 v20, v20, v28
	v_mul_f32_e32 v21, v21, v29
	v_mul_f32_e32 v22, v22, v34
	v_mul_f32_e32 v23, v23, v31
	v_mul_f32_e32 v26, v16, v38
	v_mul_f32_e32 v16, v19, v27
	v_mul_f32_e32 v20, v20, v32
	v_mul_f32_e32 v21, v21, v33
	v_mul_f32_e32 v23, v23, v35
	v_mul_f32_e32 v19, v16, v39
	v_cvt_pk_bf16_f32 v16, v20, v21
	v_cvt_pk_bf16_f32 v17, v22, v23
	v_exp_f32_e64 v22, -v8
	v_exp_f32_e64 v23, -v9
	v_cvt_pk_bf16_f32 v18, v24, v25
	v_add_co_u32_e32 v20, vcc, s61, v52
	v_exp_f32_e64 v24, -v10
	v_cvt_pk_bf16_f32 v19, v26, v19
	s_nop 0
	v_addc_co_u32_e32 v21, vcc, 0, v53, vcc
	v_exp_f32_e64 v25, -v11
	global_store_dwordx4 v[20:21], v[16:19], off
	v_add_f32_e32 v22, 1.0, v22
	v_add_f32_e32 v23, 1.0, v23
	v_exp_f32_e64 v16, -v12
	v_exp_f32_e64 v17, -v13
	v_exp_f32_e64 v18, -v14
	v_exp_f32_e64 v19, -v15
	v_rcp_f32_e32 v22, v22
	v_add_f32_e32 v24, 1.0, v24
	v_rcp_f32_e32 v23, v23
	v_add_f32_e32 v25, 1.0, v25
	v_rcp_f32_e32 v24, v24
	v_add_f32_e32 v16, 1.0, v16
	v_add_f32_e32 v17, 1.0, v17
	v_add_f32_e32 v18, 1.0, v18
	v_add_f32_e32 v19, 1.0, v19
	v_rcp_f32_e32 v25, v25
	v_mul_f32_e32 v0, v0, v8
	v_rcp_f32_e32 v16, v16
	v_rcp_f32_e32 v17, v17
	v_rcp_f32_e32 v18, v18
	v_rcp_f32_e32 v19, v19
	v_mul_f32_e32 v8, v0, v22
	v_mul_f32_e32 v0, v1, v9
	v_mul_f32_e32 v9, v0, v23
	v_mul_f32_e32 v0, v2, v10
	v_mul_f32_e32 v10, v0, v24
	v_mul_f32_e32 v0, v3, v11
	v_mul_f32_e32 v4, v4, v12
	v_mul_f32_e32 v5, v5, v13
	v_mul_f32_e32 v6, v6, v14
	v_mul_f32_e32 v7, v7, v15
	v_mul_f32_e32 v3, v0, v25
	s_andn2_b64 vcc, exec, s[44:45]
	s_mov_b64 s[4:5], -1
	v_mul_f32_e32 v4, v4, v16
	v_mul_f32_e32 v5, v5, v17
	v_mul_f32_e32 v6, v6, v18
	v_mul_f32_e32 v7, v7, v19
	v_cvt_pk_bf16_f32 v0, v4, v5
	v_cvt_pk_bf16_f32 v1, v6, v7
	v_cvt_pk_bf16_f32 v2, v8, v9
	v_cvt_pk_bf16_f32 v3, v10, v3
	global_store_dwordx4 v[20:21], v[0:3], off offset:2048
	s_cbranch_vccnz .LBB0_1649
	s_andn2_b64 vcc, exec, s[0:1]
	s_cbranch_vccnz .LBB0_1648
	s_barrier
	s_branch .LBB0_1648

; __device__ __forceinline__ unsigned cvt_pk_bf16(float lo, float hi) { unsigned r; asm volatile("v_cvt_pk_bf16_f32 %0, %1, %2" : "=v"(r) : "v"(lo), "v"(hi)); return r; }
; #define PG8_BAR __builtin_amdgcn_s_barrier()
;     __device__ __forceinline__ void half(const f32x4 (&acc)[2][4][2], int pm, int ai, int pn, int wr, int wc, int fr, int fq) const {
;         const int row0 = pm * BM + wr * 64 + fr, col0 = pn * HALF + wc * 32 + 8 * fq;
;         {
; #pragma unroll
;             for (int m = 0; m < 4; ++m) {
;                 float a[8], e[8];
; #pragma unroll
;                 for (int q = 0; q < 8; ++q) a[q] = acc[0][m][q >> 2][q & 3];
; #pragma unroll
;                 for (int q = 0; q < 8; ++q) e[q] = __builtin_amdgcn_exp2f(-a[q]);
; #pragma unroll
;                 for (int q = 0; q < 8; ++q) e[q] += 1.f;
; #pragma unroll
;                 for (int q = 0; q < 8; ++q) e[q] = __builtin_amdgcn_rcpf(e[q]);
; #pragma unroll
;                 for (int q = 0; q < 8; ++q) a[q] = a[q] * acc[1][m][q >> 2][q & 3] * e[q];
;                 u32x4 w; w.x = cvt_pk_bf16(a[0], a[1]); w.y = cvt_pk_bf16(a[2], a[3]); w.z = cvt_pk_bf16(a[4], a[5]); w.w = cvt_pk_bf16(a[6], a[7]);
;                 const int row = row0 + ai * HALF + m * 16;
;                 bf16_t* dst = O + (((size_t)(row >> 8) * (ldc >> 6) + (col0 >> 6)) * 256 + (row & 255)) * 64 + (col0 & 63);
;                 if (wt) asm volatile("global_store_dwordx4 %0, %1, off sc1\n\ts_nop 1" :: "v"(dst), "v"(w) : "memory"); else *(u32x4*)dst = w; }
;         }
; template <class Epi, class Sched, bool ALIGN_EPI = false, bool SP2 = false>
; __device__ __forceinline__ void gemm_phase(PG8_LAS unsigned char* lds, const Gemm g, const Sched& S, const Epi& E) {
;     ...
;         if constexpr (ALIGN_EPI) { if (wr == 0) PG8_BAR; }
;         if constexpr (!Epi::AFTER_DRAIN) { E(acc, cur, wr, wc, fr, fq); S.done(cur); }
.LBB0_3061:
	v_exp_f32_e64 v159, -v120
	v_exp_f32_e64 v160, -v121
	v_exp_f32_e64 v155, -v124
	v_exp_f32_e64 v156, -v125
	v_exp_f32_e64 v157, -v126
	v_exp_f32_e64 v161, -v122
	v_exp_f32_e64 v158, -v127
	v_exp_f32_e64 v162, -v123
	s_lshl_b32 s4, s38, 8
	v_add_f32_e32 v159, 1.0, v159
	s_lshl_b32 s5, s34, 7
	s_add_i32 s12, s4, s46
	v_add_f32_e32 v160, 1.0, v160
	v_rcp_f32_e32 v159, v159
	s_or_b32 s5, s5, s47
	s_ashr_i32 s12, s12, 8
	v_add_f32_e32 v155, 1.0, v155
	v_add_f32_e32 v156, 1.0, v156
	v_add_f32_e32 v157, 1.0, v157
	v_add_f32_e32 v161, 1.0, v161
	v_rcp_f32_e32 v160, v160
	s_ashr_i32 s34, s5, 6
	v_add_f32_e32 v158, 1.0, v158
	v_add_f32_e32 v162, 1.0, v162
	v_rcp_f32_e32 v155, v155
	v_rcp_f32_e32 v156, v156
	v_rcp_f32_e32 v157, v157
	v_rcp_f32_e32 v161, v161
	s_mulk_i32 s12, 0x58
	s_ashr_i32 s35, s34, 31
	v_rcp_f32_e32 v158, v158
	v_rcp_f32_e32 v162, v162
	v_mul_f32_e32 v112, v112, v120
	s_ashr_i32 s5, s12, 31
	v_mul_f32_e32 v120, v112, v159
	v_mul_f32_e32 v112, v113, v121
	s_add_u32 s12, s12, s34
	v_mul_f32_e32 v116, v116, v124
	v_mul_f32_e32 v117, v117, v125
	v_mul_f32_e32 v118, v118, v126
	v_mul_f32_e32 v121, v112, v160
	v_mul_f32_e32 v112, v114, v122
	s_addc_u32 s13, s5, s35
	v_mul_f32_e32 v116, v116, v155
	v_mul_f32_e32 v117, v117, v156
	v_mul_f32_e32 v118, v118, v157
	v_mul_f32_e32 v119, v119, v127
	v_mul_f32_e32 v122, v112, v161
	v_mul_f32_e32 v112, v115, v123
	s_lshl_b64 s[12:13], s[12:13], 15
	v_mul_f32_e32 v119, v119, v158
	v_mul_f32_e32 v115, v112, v162
	v_cvt_pk_bf16_f32 v112, v116, v117
	v_cvt_pk_bf16_f32 v113, v118, v119
	v_lshl_add_u64 v[116:117], v[138:139], 0, s[12:13]
	v_exp_f32_e64 v118, -v104
	v_lshl_add_u64 v[116:117], v[116:117], 0, v[136:137]
	v_exp_f32_e64 v119, -v105
	v_cvt_pk_bf16_f32 v114, v120, v121
	v_cvt_pk_bf16_f32 v115, v122, v115
	global_store_dwordx4 v[116:117], v[112:115], off
	v_exp_f32_e64 v120, -v106
	v_exp_f32_e64 v121, -v107
	v_exp_f32_e64 v112, -v108
	v_exp_f32_e64 v113, -v109
	v_exp_f32_e64 v114, -v110
	v_exp_f32_e64 v115, -v111
	v_add_f32_e32 v118, 1.0, v118
	v_add_f32_e32 v119, 1.0, v119
	v_rcp_f32_e32 v118, v118
	v_add_f32_e32 v112, 1.0, v112
	v_add_f32_e32 v120, 1.0, v120
	v_rcp_f32_e32 v119, v119
	v_add_f32_e32 v113, 1.0, v113
	v_add_f32_e32 v121, 1.0, v121
	v_rcp_f32_e32 v112, v112
	v_rcp_f32_e32 v120, v120
	v_add_f32_e32 v114, 1.0, v114
	v_add_f32_e32 v115, 1.0, v115
	v_rcp_f32_e32 v113, v113
	v_rcp_f32_e32 v121, v121
	v_mul_f32_e32 v96, v96, v104
	v_rcp_f32_e32 v114, v114
	v_rcp_f32_e32 v115, v115
	v_mul_f32_e32 v104, v96, v118
	v_mul_f32_e32 v96, v97, v105
	v_mul_f32_e32 v100, v100, v108
	v_mul_f32_e32 v105, v96, v119
	v_mul_f32_e32 v96, v98, v106
	v_mul_f32_e32 v100, v100, v112
	v_mul_f32_e32 v101, v101, v109
	v_mul_f32_e32 v106, v96, v120
	v_mul_f32_e32 v96, v99, v107
	v_mul_f32_e32 v101, v101, v113
	v_mul_f32_e32 v102, v102, v110
	v_mul_f32_e32 v103, v103, v111
	v_mul_f32_e32 v99, v96, v121
	v_cvt_pk_bf16_f32 v96, v100, v101
	v_exp_f32_e64 v100, -v88
	v_mul_f32_e32 v102, v102, v114
	v_mul_f32_e32 v103, v103, v115
	v_cvt_pk_bf16_f32 v97, v102, v103
	v_cvt_pk_bf16_f32 v98, v104, v105
	v_exp_f32_e64 v101, -v89
	v_cvt_pk_bf16_f32 v99, v106, v99
	global_store_dwordx4 v[116:117], v[96:99], off offset:2048
	v_exp_f32_e64 v102, -v90
	v_exp_f32_e64 v103, -v91
	v_exp_f32_e64 v96, -v92
	v_exp_f32_e64 v98, -v94
	v_exp_f32_e64 v97, -v93
	v_exp_f32_e64 v99, -v95
	v_add_f32_e32 v100, 1.0, v100
	v_add_f32_e32 v101, 1.0, v101
	v_rcp_f32_e32 v100, v100
	v_add_f32_e32 v96, 1.0, v96
	v_add_f32_e32 v98, 1.0, v98
	v_add_f32_e32 v102, 1.0, v102
	v_rcp_f32_e32 v101, v101
	v_add_f32_e32 v97, 1.0, v97
	v_add_f32_e32 v99, 1.0, v99
	v_add_f32_e32 v103, 1.0, v103
	v_rcp_f32_e32 v96, v96
	v_rcp_f32_e32 v98, v98
	v_rcp_f32_e32 v102, v102
	v_rcp_f32_e32 v97, v97
	v_rcp_f32_e32 v99, v99
	v_rcp_f32_e32 v103, v103
	v_mul_f32_e32 v80, v80, v88
	v_mul_f32_e32 v88, v80, v100
	v_mul_f32_e32 v80, v81, v89
	v_mul_f32_e32 v84, v84, v92
	v_mul_f32_e32 v86, v86, v94
	v_mul_f32_e32 v89, v80, v101
	v_mul_f32_e32 v80, v82, v90
	v_mul_f32_e32 v84, v84, v96
	v_mul_f32_e32 v85, v85, v93
	v_mul_f32_e32 v86, v86, v98
	v_mul_f32_e32 v87, v87, v95
	v_mul_f32_e32 v90, v80, v102
	v_mul_f32_e32 v80, v83, v91
	v_mul_f32_e32 v85, v85, v97
	v_mul_f32_e32 v87, v87, v99
	v_mul_f32_e32 v83, v80, v103
	v_cvt_pk_bf16_f32 v80, v84, v85
	v_cvt_pk_bf16_f32 v81, v86, v87
	v_add_co_u32_e32 v84, vcc, s52, v116
	v_exp_f32_e64 v86, -v72
	s_nop 0
	v_addc_co_u32_e32 v85, vcc, 0, v117, vcc
	v_exp_f32_e64 v87, -v73
	v_cvt_pk_bf16_f32 v82, v88, v89
	v_cvt_pk_bf16_f32 v83, v90, v83
	global_store_dwordx4 v[84:85], v[80:83], off
	v_exp_f32_e64 v88, -v74
	v_exp_f32_e64 v89, -v75
	v_exp_f32_e64 v81, -v77
	v_exp_f32_e64 v80, -v76
	v_exp_f32_e64 v82, -v78
	v_exp_f32_e64 v83, -v79
	v_add_f32_e32 v86, 1.0, v86
	v_add_f32_e32 v87, 1.0, v87
	v_rcp_f32_e32 v86, v86
	v_add_f32_e32 v81, 1.0, v81
	v_add_f32_e32 v88, 1.0, v88
	v_rcp_f32_e32 v87, v87
	v_add_f32_e32 v80, 1.0, v80
	v_add_f32_e32 v82, 1.0, v82
	v_add_f32_e32 v89, 1.0, v89
	v_rcp_f32_e32 v81, v81
	v_rcp_f32_e32 v88, v88
	v_add_f32_e32 v83, 1.0, v83
	v_rcp_f32_e32 v80, v80
	v_rcp_f32_e32 v82, v82
	v_rcp_f32_e32 v89, v89
	v_mul_f32_e32 v64, v64, v72
	v_rcp_f32_e32 v83, v83
	v_mul_f32_e32 v72, v64, v86
	v_mul_f32_e32 v64, v65, v73
	v_mul_f32_e32 v69, v69, v77
	v_mul_f32_e32 v73, v64, v87
	v_mul_f32_e32 v64, v66, v74
	v_mul_f32_e32 v68, v68, v76
	v_mul_f32_e32 v69, v69, v81
	v_mul_f32_e32 v70, v70, v78
	v_mul_f32_e32 v74, v64, v88
	v_mul_f32_e32 v64, v67, v75
	v_mul_f32_e32 v68, v68, v80
	v_mul_f32_e32 v70, v70, v82
	v_mul_f32_e32 v71, v71, v79
	v_mul_f32_e32 v67, v64, v89
	v_cvt_pk_bf16_f32 v64, v68, v69
	v_exp_f32_e64 v69, -v56
	v_mul_f32_e32 v71, v71, v83
	v_cvt_pk_bf16_f32 v65, v70, v71
	v_exp_f32_e64 v70, -v57
	v_cvt_pk_bf16_f32 v66, v72, v73
	v_cvt_pk_bf16_f32 v67, v74, v67
	global_store_dwordx4 v[84:85], v[64:67], off offset:2048
	s_and_b64 vcc, exec, s[18:19]
	s_cbranch_vccz .Lepi_3061
	s_barrier
; __device__ __forceinline__ unsigned cvt_pk_bf16(float lo, float hi) { unsigned r; asm volatile("v_cvt_pk_bf16_f32 %0, %1, %2" : "=v"(r) : "v"(lo), "v"(hi)); return r; }
; #define PG8_BAR __builtin_amdgcn_s_barrier()
;     __device__ __forceinline__ void half(const f32x4 (&acc)[2][4][2], int pm, int ai, int pn, int wr, int wc, int fr, int fq) const {
;         const int row0 = pm * BM + wr * 64 + fr, col0 = pn * HALF + wc * 32 + 8 * fq;
;         {
; #pragma unroll
;             for (int m = 0; m < 4; ++m) {
;                 float a[8], e[8];
; #pragma unroll
;                 for (int q = 0; q < 8; ++q) a[q] = acc[0][m][q >> 2][q & 3];
; #pragma unroll
;                 for (int q = 0; q < 8; ++q) e[q] = __builtin_amdgcn_exp2f(-a[q]);
; #pragma unroll
;                 for (int q = 0; q < 8; ++q) e[q] += 1.f;
; #pragma unroll
;                 for (int q = 0; q < 8; ++q) e[q] = __builtin_amdgcn_rcpf(e[q]);
; #pragma unroll
;                 for (int q = 0; q < 8; ++q) a[q] = a[q] * acc[1][m][q >> 2][q & 3] * e[q];
;                 u32x4 w; w.x = cvt_pk_bf16(a[0], a[1]); w.y = cvt_pk_bf16(a[2], a[3]); w.z = cvt_pk_bf16(a[4], a[5]); w.w = cvt_pk_bf16(a[6], a[7]);
;                 const int row = row0 + ai * HALF + m * 16;
;                 bf16_t* dst = O + (((size_t)(row >> 8) * (ldc >> 6) + (col0 >> 6)) * 256 + (row & 255)) * 64 + (col0 & 63);
;                 if (wt) asm volatile("global_store_dwordx4 %0, %1, off sc1\n\ts_nop 1" :: "v"(dst), "v"(w) : "memory"); else *(u32x4*)dst = w; }
;         }
; template <class Epi, class Sched, bool ALIGN_EPI = false, bool SP2 = false>
; __device__ __forceinline__ void gemm_phase(PG8_LAS unsigned char* lds, const Gemm g, const Sched& S, const Epi& E) {
;     ...
;         if (!has_next) break;
; #pragma unroll
;         for (int a = 0; a < 2; ++a)
; #pragma unroll
;             for (int b = 0; b < 2; ++b)
; #pragma unroll
;                 for (int m = 0; m < 4; ++m)
; #pragma unroll
;                     for (int n = 0; n < 2; ++n) acc[a][b][m][n] = (f32x4){0.f, 0.f, 0.f, 0.f};
;         cur = nxt; cA = nA; cB = nB; ++ui;
;         if constexpr (ALIGN_EPI) { if (wr == 1) PG8_BAR; }
.Lepi_3061:
	v_exp_f32_e64 v71, -v58
	v_exp_f32_e64 v72, -v59
	v_exp_f32_e64 v65, -v60
	v_exp_f32_e64 v66, -v61
	v_add_f32_e32 v69, 1.0, v69
	v_add_f32_e32 v70, 1.0, v70
	v_rcp_f32_e32 v69, v69
	v_exp_f32_e64 v67, -v62
	v_add_f32_e32 v65, 1.0, v65
	v_add_f32_e32 v71, 1.0, v71
	v_rcp_f32_e32 v70, v70
	v_exp_f32_e64 v68, -v63
	v_add_f32_e32 v66, 1.0, v66
	v_add_f32_e32 v72, 1.0, v72
	v_rcp_f32_e32 v65, v65
	v_rcp_f32_e32 v71, v71
	v_rcp_f32_e32 v66, v66
	v_rcp_f32_e32 v72, v72
	v_mul_f32_e32 v48, v48, v56
	v_mul_f32_e32 v56, v48, v69
	v_mul_f32_e32 v48, v49, v57
	v_add_u32_e32 v64, s4, v151
	v_add_f32_e32 v67, 1.0, v67
	v_mul_f32_e32 v52, v52, v60
	v_mul_f32_e32 v57, v48, v70
	v_mul_f32_e32 v48, v50, v58
	v_lshrrev_b32_e32 v64, 8, v64
	v_add_f32_e32 v68, 1.0, v68
	v_rcp_f32_e32 v67, v67
	v_mul_f32_e32 v52, v52, v65
	v_mul_f32_e32 v53, v53, v61
	v_mul_f32_e32 v58, v48, v71
	v_mul_f32_e32 v48, v51, v59
	v_rcp_f32_e32 v68, v68
	v_mul_f32_e32 v53, v53, v66
	v_mul_f32_e32 v51, v48, v72
	v_cvt_pk_bf16_f32 v48, v52, v53
	v_mul_i32_i24_e32 v52, 0x58, v64
	v_ashrrev_i32_e32 v53, 31, v52
	v_mul_f32_e32 v54, v54, v62
	v_lshl_add_u64 v[52:53], v[52:53], 0, s[34:35]
	v_mul_f32_e32 v54, v54, v67
	v_mul_f32_e32 v55, v55, v63
	v_lshlrev_b64 v[52:53], 15, v[52:53]
	v_mul_f32_e32 v55, v55, v68
	v_cvt_pk_bf16_f32 v49, v54, v55
	v_lshl_add_u64 v[52:53], v[140:141], 0, v[52:53]
	v_exp_f32_e64 v54, -v40
	v_lshl_add_u64 v[52:53], v[52:53], 0, v[136:137]
	v_exp_f32_e64 v55, -v41
	v_cvt_pk_bf16_f32 v50, v56, v57
	v_cvt_pk_bf16_f32 v51, v58, v51
	global_store_dwordx4 v[52:53], v[48:51], off
	v_exp_f32_e64 v56, -v42
	v_exp_f32_e64 v57, -v43
	v_exp_f32_e64 v48, -v44
	v_exp_f32_e64 v49, -v45
	v_exp_f32_e64 v50, -v46
	v_exp_f32_e64 v51, -v47
	v_add_f32_e32 v54, 1.0, v54
	v_add_f32_e32 v55, 1.0, v55
	v_rcp_f32_e32 v54, v54
	v_add_f32_e32 v48, 1.0, v48
	v_add_f32_e32 v56, 1.0, v56
	v_rcp_f32_e32 v55, v55
	v_add_f32_e32 v49, 1.0, v49
	v_add_f32_e32 v57, 1.0, v57
	v_rcp_f32_e32 v48, v48
	v_rcp_f32_e32 v56, v56
	v_add_f32_e32 v50, 1.0, v50
	v_add_f32_e32 v51, 1.0, v51
	v_rcp_f32_e32 v49, v49
	v_rcp_f32_e32 v57, v57
	v_mul_f32_e32 v32, v32, v40
	v_rcp_f32_e32 v50, v50
	v_rcp_f32_e32 v51, v51
	v_mul_f32_e32 v40, v32, v54
	v_mul_f32_e32 v32, v33, v41
	v_mul_f32_e32 v36, v36, v44
	v_mul_f32_e32 v41, v32, v55
	v_mul_f32_e32 v32, v34, v42
	v_mul_f32_e32 v36, v36, v48
	v_mul_f32_e32 v37, v37, v45
	v_mul_f32_e32 v42, v32, v56
	v_mul_f32_e32 v32, v35, v43
	v_mul_f32_e32 v37, v37, v49
	v_mul_f32_e32 v38, v38, v46
	v_mul_f32_e32 v39, v39, v47
	v_mul_f32_e32 v35, v32, v57
	v_cvt_pk_bf16_f32 v32, v36, v37
	v_exp_f32_e64 v36, -v24
	v_mul_f32_e32 v38, v38, v50
	v_mul_f32_e32 v39, v39, v51
	v_cvt_pk_bf16_f32 v33, v38, v39
	v_cvt_pk_bf16_f32 v34, v40, v41
	v_exp_f32_e64 v37, -v25
	v_cvt_pk_bf16_f32 v35, v42, v35
	global_store_dwordx4 v[52:53], v[32:35], off offset:2048
	v_exp_f32_e64 v38, -v26
	v_exp_f32_e64 v39, -v27
	v_exp_f32_e64 v34, -v30
	v_exp_f32_e64 v32, -v28
	v_exp_f32_e64 v33, -v29
	v_exp_f32_e64 v35, -v31
	v_add_f32_e32 v36, 1.0, v36
	v_add_f32_e32 v37, 1.0, v37
	v_rcp_f32_e32 v36, v36
	v_add_f32_e32 v34, 1.0, v34
	v_add_f32_e32 v38, 1.0, v38
	v_rcp_f32_e32 v37, v37
	v_add_f32_e32 v32, 1.0, v32
	v_add_f32_e32 v33, 1.0, v33
	v_add_f32_e32 v35, 1.0, v35
	v_add_f32_e32 v39, 1.0, v39
	v_rcp_f32_e32 v34, v34
	v_rcp_f32_e32 v38, v38
	v_rcp_f32_e32 v32, v32
	v_rcp_f32_e32 v33, v33
	v_rcp_f32_e32 v35, v35
	v_rcp_f32_e32 v39, v39
	v_mul_f32_e32 v16, v16, v24
	v_mul_f32_e32 v24, v16, v36
	v_mul_f32_e32 v16, v17, v25
	v_mul_f32_e32 v22, v22, v30
	v_mul_f32_e32 v25, v16, v37
	v_mul_f32_e32 v16, v18, v26
	v_mul_f32_e32 v20, v20, v28
	v_mul_f32_e32 v21, v21, v29
	v_mul_f32_e32 v22, v22, v34
	v_mul_f32_e32 v23, v23, v31
	v_mul_f32_e32 v26, v16, v38
	v_mul_f32_e32 v16, v19, v27
	v_mul_f32_e32 v20, v20, v32
	v_mul_f32_e32 v21, v21, v33
	v_mul_f32_e32 v23, v23, v35
	v_mul_f32_e32 v19, v16, v39
	v_cvt_pk_bf16_f32 v16, v20, v21
	v_cvt_pk_bf16_f32 v17, v22, v23
	v_exp_f32_e64 v22, -v8
	v_exp_f32_e64 v23, -v9
	v_cvt_pk_bf16_f32 v18, v24, v25
	v_add_co_u32_e32 v20, vcc, s52, v52
	v_exp_f32_e64 v24, -v10
	v_cvt_pk_bf16_f32 v19, v26, v19
	s_nop 0
	v_addc_co_u32_e32 v21, vcc, 0, v53, vcc
	v_exp_f32_e64 v25, -v11
	global_store_dwordx4 v[20:21], v[16:19], off
	v_add_f32_e32 v22, 1.0, v22
	v_add_f32_e32 v23, 1.0, v23
	v_exp_f32_e64 v16, -v12
	v_exp_f32_e64 v17, -v13
	v_exp_f32_e64 v18, -v14
	v_exp_f32_e64 v19, -v15
	v_rcp_f32_e32 v22, v22
	v_add_f32_e32 v24, 1.0, v24
	v_rcp_f32_e32 v23, v23
	v_add_f32_e32 v25, 1.0, v25
	v_rcp_f32_e32 v24, v24
	v_add_f32_e32 v16, 1.0, v16
	v_add_f32_e32 v17, 1.0, v17
	v_add_f32_e32 v18, 1.0, v18
	v_add_f32_e32 v19, 1.0, v19
	v_rcp_f32_e32 v25, v25
	v_mul_f32_e32 v0, v0, v8
	v_rcp_f32_e32 v16, v16
	v_rcp_f32_e32 v17, v17
	v_rcp_f32_e32 v18, v18
	v_rcp_f32_e32 v19, v19
	v_mul_f32_e32 v8, v0, v22
	v_mul_f32_e32 v0, v1, v9
	v_mul_f32_e32 v9, v0, v23
	v_mul_f32_e32 v0, v2, v10
	v_mul_f32_e32 v10, v0, v24
	v_mul_f32_e32 v0, v3, v11
	v_mul_f32_e32 v4, v4, v12
	v_mul_f32_e32 v5, v5, v13
	v_mul_f32_e32 v6, v6, v14
	v_mul_f32_e32 v7, v7, v15
	v_mul_f32_e32 v3, v0, v25
	s_andn2_b64 vcc, exec, s[36:37]
	s_mov_b64 s[4:5], -1
	v_mul_f32_e32 v4, v4, v16
	v_mul_f32_e32 v5, v5, v17
	v_mul_f32_e32 v6, v6, v18
	v_mul_f32_e32 v7, v7, v19
	v_cvt_pk_bf16_f32 v0, v4, v5
	v_cvt_pk_bf16_f32 v1, v6, v7
	v_cvt_pk_bf16_f32 v2, v8, v9
	v_cvt_pk_bf16_f32 v3, v10, v3
	global_store_dwordx4 v[20:21], v[0:3], off offset:2048
	s_cbranch_vccnz .LBB0_3050
	s_andn2_b64 vcc, exec, s[0:1]
	s_cbranch_vccnz .LBB0_3049
	s_barrier
	s_branch .LBB0_3049
